# baseline (speedup 1.0000x reference)
; #define GAS __attribute__((address_space(1)))
; __device__ __forceinline__ int otid() { int t = threadIdx.x; asm volatile("" : "+v"(t)); return t; }
; #define WAIT_V(n) asm volatile("s_waitcnt vmcnt(" #n ")" ::: "memory")
; #define BAR __builtin_amdgcn_s_barrier()
; template <int K, int LD = K>
; __device__ __forceinline__ void gemm_main(const GAS bf16* A, const GAS bf16* Bt, int brow, int bcol, f32x4 (&acc)[2][2][4][2]) {
;     ...
;   const int tid_ = otid();
;     ...
;   const int wid = tid_ >> 6, lane = tid_ & 63, wr = wid >> 2, wc = wid & 3, fr = lane & 15, fq = lane >> 4;
; #pragma unroll
;   for (int a = 0; a < 2; ++a)
; #pragma unroll
;     for (int b = 0; b < 2; ++b)
; #pragma unroll
;       for (int m = 0; m < 4; ++m)
; #pragma unroll
;         for (int n = 0; n < 2; ++n) acc[a][b][m][n] = f32x4{0.f, 0.f, 0.f, 0.f};
;   bf16x8 At[4][2], B0[2][2], B1[2][2];
;   unsigned so0, so1;
;   { int r_, c_; stage_rc(tid_ * 16, r_, c_); so0 = (unsigned)(r_ * LD + c_) * 2u; stage_rc(tid_ * 16 + 8192, r_, c_); so1 = (unsigned)(r_ * LD + c_) * 2u; }
;   const GAS char* pA0 = (const GAS char*)A + (long)brow * LD * 2; const GAS char* pA1 = pA0 + (long)HALF * LD * 2;
;   const GAS char* pB0 = (const GAS char*)Bt + (long)bcol * LD * 2; const GAS char* pB1 = pB0 + (long)HALF * LD * 2;
;   asm volatile("" : "+s"(pA0), "+s"(pA1), "+s"(pB0), "+s"(pB1));
;   constexpr int nt = K / BK;
;   static_assert(K % 128 == 0 && K >= 256, "K");
;   if (wr == 1) BAR;
;   WAIT_V(0); BAR;
;   BAR;
.LBB0_88:
	s_or_b64 exec, exec, s[24:25]
	v_bfe_i32 v7, v136, 27, 1
	v_lshlrev_b32_e32 v5, 4, v136
	v_lshrrev_b32_e32 v7, 22, v7
	v_add_u32_e32 v7, v5, v7
	v_and_b32_e32 v7, 0xfffffc00, v7
	v_sub_u32_e32 v7, v5, v7
	v_lshrrev_b32_e32 v8, 4, v7
	v_bitop3_b32 v8, v8, v7, 32 bitop3:0x6c
	v_ashrrev_i32_e32 v7, 31, v7
	v_ashrrev_i32_e32 v6, 31, v136
	v_lshrrev_b32_e32 v7, 26, v7
	v_lshrrev_b32_e32 v6, 26, v6
	v_add_u32_e32 v7, v8, v7
	v_add_u32_e32 v6, v136, v6
	v_ashrrev_i32_e32 v7, 6, v7
	v_ashrrev_i32_e32 v6, 6, v6
	v_mul_i32_i24_e32 v10, 64, v7
	v_lshlrev_b32_e32 v9, 3, v6
	v_lshlrev_b32_e32 v6, 5, v6
	v_sub_u32_e32 v8, v8, v10
	v_and_b32_e32 v9, 0x1ffff0, v9
	v_and_b32_e32 v6, 32, v6
	v_ashrrev_i16_sdwa v8, v134, sext(v8) dst_sel:DWORD dst_unused:UNUSED_PAD src0_sel:DWORD src1_sel:BYTE_0
	v_add_u32_sdwa v6, v6, sext(v8) dst_sel:DWORD dst_unused:UNUSED_PAD src0_sel:DWORD src1_sel:WORD_0
	v_add_lshl_u32 v7, v7, v9, 11
	v_lshl_add_u32 v130, v6, 1, v7
	v_add_u32_e32 v6, 0x2000, v5
	v_ashrrev_i32_e32 v7, 31, v6
	v_lshrrev_b32_e32 v7, 22, v7
	v_add_u32_e32 v7, v6, v7
	v_ashrrev_i32_e32 v7, 10, v7
	v_mul_i32_i24_e32 v8, 0x400, v7
	v_sub_u32_e32 v6, v6, v8
	v_lshrrev_b32_e32 v8, 4, v6
	v_bitop3_b32 v6, v8, v6, 32 bitop3:0x6c
	v_ashrrev_i32_e32 v9, 31, v6
	v_lshrrev_b32_e32 v9, 26, v9
	v_add_u32_e32 v9, v6, v9
	v_lshrrev_b32_e32 v10, 6, v9
	v_and_b32_e32 v9, 0xc0, v9
	v_lshlrev_b32_e32 v8, 3, v7
	v_lshlrev_b32_e32 v7, 5, v7
	v_sub_u32_e32 v6, v6, v9
	v_and_b32_e32 v8, 0x1ffff0, v8
	v_and_b32_e32 v7, 32, v7
	v_ashrrev_i16_sdwa v6, v134, sext(v6) dst_sel:DWORD dst_unused:UNUSED_PAD src0_sel:DWORD src1_sel:BYTE_0
	v_add_u32_sdwa v6, v7, sext(v6) dst_sel:DWORD dst_unused:UNUSED_PAD src0_sel:DWORD src1_sel:WORD_0
	v_add_lshl_u32 v7, v10, v8, 11
	v_and_b32_e32 v3, 15, v136
	v_lshl_add_u32 v132, v6, 1, v7
	v_lshlrev_b32_e32 v6, 2, v136
	v_and_b32_e32 v4, 48, v136
	v_lshlrev_b32_e32 v3, 6, v3
	v_and_b32_e32 v6, 32, v6
	v_lshlrev_b32_e32 v11, 6, v136
	v_bitop3_b32 v3, v3, v6, v4 bitop3:0x36
	v_lshlrev_b32_e32 v13, 13, v2
	v_and_or_b32 v2, v11, s38, v4
	v_add_u32_e32 v7, s29, v3
	v_add_u32_e32 v8, s30, v3
	v_add_u32_e32 v9, s31, v3
	v_add_u32_e32 v10, s33, v3
	v_and_b32_e32 v12, 0x3000, v11
	v_add_u32_e32 v3, 0x100, v3
	v_xad_u32 v4, v2, v6, s34
	v_or_b32_e32 v6, 0x800, v13
	v_or_b32_e32 v11, 0x1000, v13
	v_or_b32_e32 v14, 0x1800, v13
	v_mov_b32_e32 v2, 0
	v_add_u32_e32 v145, 0x100, v5
	v_add_u32_e32 v146, s29, v5
	v_add_u32_e32 v147, s30, v5
	v_add_u32_e32 v148, s31, v5
	v_add_u32_e32 v149, s33, v5
	v_mov_b32_e32 v133, v131
	s_mov_b32 s17, -2
	v_add_u32_e32 v144, v7, v12
	v_add_u32_e32 v140, v3, v13
	v_add_u32_e32 v139, v4, v6
	v_add_u32_e32 v138, v4, v11
	v_add_u32_e32 v137, v4, v14
	v_add_u32_e32 v143, v8, v12
	v_add_u32_e32 v142, v9, v12
	v_add_u32_e32 v141, v10, v12
	v_mov_b32_e32 v3, v2
	v_mov_b32_e32 v4, v2
	v_mov_b32_e32 v5, v2
	v_mov_b32_e32 v6, v2
	v_mov_b32_e32 v7, v2
	v_mov_b32_e32 v8, v2
	v_mov_b32_e32 v9, v2
	v_mov_b32_e32 v10, v2
	v_mov_b32_e32 v11, v2
	v_mov_b32_e32 v12, v2
	v_mov_b32_e32 v13, v2
	v_mov_b32_e32 v14, v2
	v_mov_b32_e32 v15, v2
	v_mov_b32_e32 v16, v2
	v_mov_b32_e32 v17, v2
	v_mov_b32_e32 v18, v2
	v_mov_b32_e32 v19, v2
	v_mov_b32_e32 v20, v2
	v_mov_b32_e32 v21, v2
	v_mov_b32_e32 v22, v2
	v_mov_b32_e32 v23, v2
	v_mov_b32_e32 v24, v2
	v_mov_b32_e32 v25, v2
	v_mov_b32_e32 v26, v2
	v_mov_b32_e32 v27, v2
	v_mov_b32_e32 v28, v2
	v_mov_b32_e32 v29, v2
	v_mov_b32_e32 v30, v2
	v_mov_b32_e32 v31, v2
	v_mov_b32_e32 v32, v2
	v_mov_b32_e32 v33, v2
	v_mov_b32_e32 v34, v2
	v_mov_b32_e32 v35, v2
	v_mov_b32_e32 v36, v2
	v_mov_b32_e32 v37, v2
	v_mov_b32_e32 v38, v2
	v_mov_b32_e32 v39, v2
	v_mov_b32_e32 v40, v2
	v_mov_b32_e32 v41, v2
	v_mov_b32_e32 v42, v2
	v_mov_b32_e32 v43, v2
	v_mov_b32_e32 v44, v2
	v_mov_b32_e32 v45, v2
	v_mov_b32_e32 v46, v2
	v_mov_b32_e32 v47, v2
	v_mov_b32_e32 v48, v2
	v_mov_b32_e32 v49, v2
	v_mov_b32_e32 v50, v2
	v_mov_b32_e32 v51, v2
	v_mov_b32_e32 v52, v2
	v_mov_b32_e32 v53, v2
	v_mov_b32_e32 v54, v2
	v_mov_b32_e32 v55, v2
	v_mov_b32_e32 v56, v2
	v_mov_b32_e32 v57, v2
	v_mov_b32_e32 v58, v2
	v_mov_b32_e32 v59, v2
	v_mov_b32_e32 v60, v2
	v_mov_b32_e32 v61, v2
	v_mov_b32_e32 v62, v2
	v_mov_b32_e32 v63, v2
	v_mov_b32_e32 v64, v2
	v_mov_b32_e32 v65, v2
	v_mov_b32_e32 v66, v2
	v_mov_b32_e32 v67, v2
	v_mov_b32_e32 v68, v2
	v_mov_b32_e32 v69, v2
	v_mov_b32_e32 v70, v2
	v_mov_b32_e32 v71, v2
	v_mov_b32_e32 v72, v2
	v_mov_b32_e32 v73, v2
	v_mov_b32_e32 v74, v2
	v_mov_b32_e32 v75, v2
	v_mov_b32_e32 v76, v2
	v_mov_b32_e32 v77, v2
	v_mov_b32_e32 v78, v2
	v_mov_b32_e32 v79, v2
	v_mov_b32_e32 v80, v2
	v_mov_b32_e32 v81, v2
	v_mov_b32_e32 v82, v2
	v_mov_b32_e32 v83, v2
	v_mov_b32_e32 v84, v2
	v_mov_b32_e32 v85, v2
	v_mov_b32_e32 v86, v2
	v_mov_b32_e32 v87, v2
	v_mov_b32_e32 v88, v2
	v_mov_b32_e32 v89, v2
	v_mov_b32_e32 v90, v2
	v_mov_b32_e32 v91, v2
	v_mov_b32_e32 v92, v2
	v_mov_b32_e32 v93, v2
	v_mov_b32_e32 v94, v2
	v_mov_b32_e32 v95, v2
	v_mov_b32_e32 v96, v2
	v_mov_b32_e32 v97, v2
	v_mov_b32_e32 v98, v2
	v_mov_b32_e32 v99, v2
	v_mov_b32_e32 v100, v2
	v_mov_b32_e32 v101, v2
	v_mov_b32_e32 v102, v2
	v_mov_b32_e32 v103, v2
	v_mov_b32_e32 v104, v2
	v_mov_b32_e32 v105, v2
	v_mov_b32_e32 v106, v2
	v_mov_b32_e32 v107, v2
	v_mov_b32_e32 v108, v2
	v_mov_b32_e32 v109, v2
	v_mov_b32_e32 v110, v2
	v_mov_b32_e32 v111, v2
	v_mov_b32_e32 v112, v2
	v_mov_b32_e32 v113, v2
	v_mov_b32_e32 v114, v2
	v_mov_b32_e32 v115, v2
	v_mov_b32_e32 v116, v2
	v_mov_b32_e32 v117, v2
	v_mov_b32_e32 v118, v2
	v_mov_b32_e32 v119, v2
	v_mov_b32_e32 v120, v2
	v_mov_b32_e32 v121, v2
	v_mov_b32_e32 v122, v2
	v_mov_b32_e32 v123, v2
	v_mov_b32_e32 v124, v2
	v_mov_b32_e32 v125, v2
	v_mov_b32_e32 v126, v2
	v_mov_b32_e32 v127, v2
	v_mov_b32_e32 v128, v2
	v_mov_b32_e32 v129, v2
	v_add_u32_e32 v151, 0xc000, v145
	v_add_u32_e32 v150, 0xe000, v145
	v_add_u32_e32 v152, 0x2000, v145
	v_add_u32_e32 v153, 0x4000, v145
	v_add_u32_e32 v154, 0x6000, v145
	v_add_u32_e32 v155, 0x8000, v145
	v_add_u32_e32 v156, 0xa000, v145
	v_add_u32_e32 v157, 0x2000, v146
	v_add_u32_e32 v158, 0x2000, v147
	v_add_u32_e32 v159, 0x2000, v148
	v_add_u32_e32 v160, 0x2000, v149
	s_waitcnt vmcnt(0)
	s_barrier
	s_barrier

; #define GAS __attribute__((address_space(1)))
; __device__ __forceinline__ int otid() { int t = threadIdx.x; asm volatile("" : "+v"(t)); return t; }
; #define WAIT_V(n) asm volatile("s_waitcnt vmcnt(" #n ")" ::: "memory")
; #define BAR __builtin_amdgcn_s_barrier()
; template <int K, int LD = K>
; __device__ __forceinline__ void gemm_main(const GAS bf16* A, const GAS bf16* Bt, int brow, int bcol, f32x4 (&acc)[2][2][4][2]) {
;     ...
;   const int tid_ = otid();
;     ...
;   const int wid = tid_ >> 6, lane = tid_ & 63, wr = wid >> 2, wc = wid & 3, fr = lane & 15, fq = lane >> 4;
; #pragma unroll
;   for (int a = 0; a < 2; ++a)
; #pragma unroll
;     for (int b = 0; b < 2; ++b)
; #pragma unroll
;       for (int m = 0; m < 4; ++m)
; #pragma unroll
;         for (int n = 0; n < 2; ++n) acc[a][b][m][n] = f32x4{0.f, 0.f, 0.f, 0.f};
;   bf16x8 At[4][2], B0[2][2], B1[2][2];
;   unsigned so0, so1;
;   { int r_, c_; stage_rc(tid_ * 16, r_, c_); so0 = (unsigned)(r_ * LD + c_) * 2u; stage_rc(tid_ * 16 + 8192, r_, c_); so1 = (unsigned)(r_ * LD + c_) * 2u; }
;   const GAS char* pA0 = (const GAS char*)A + (long)brow * LD * 2; const GAS char* pA1 = pA0 + (long)HALF * LD * 2;
;   const GAS char* pB0 = (const GAS char*)Bt + (long)bcol * LD * 2; const GAS char* pB1 = pB0 + (long)HALF * LD * 2;
;   asm volatile("" : "+s"(pA0), "+s"(pA1), "+s"(pB0), "+s"(pB1));
;   constexpr int nt = K / BK;
;   static_assert(K % 128 == 0 && K >= 256, "K");
;   if (wr == 1) BAR;
;   WAIT_V(0); BAR;
;   BAR;
.LBB0_229:
	s_or_b64 exec, exec, s[22:23]
	v_bfe_i32 v7, v134, 27, 1
	v_lshlrev_b32_e32 v5, 4, v134
	v_lshrrev_b32_e32 v7, 22, v7
	v_add_u32_e32 v7, v5, v7
	v_and_b32_e32 v7, 0xfffffc00, v7
	v_ashrrev_i32_e32 v6, 31, v134
	v_sub_u32_e32 v7, v5, v7
	v_lshrrev_b32_e32 v6, 26, v6
	v_lshrrev_b32_e32 v8, 4, v7
	v_add_u32_e32 v6, v134, v6
	v_bitop3_b32 v8, v8, v7, 32 bitop3:0x6c
	v_ashrrev_i32_e32 v7, 31, v7
	v_ashrrev_i32_e32 v6, 6, v6
	v_lshrrev_b32_e32 v7, 26, v7
	v_lshlrev_b32_e32 v9, 3, v6
	v_add_u32_e32 v7, v8, v7
	v_and_b32_e32 v9, 0x3fffff0, v9
	v_ashrrev_i32_e32 v7, 6, v7
	v_add_u32_e32 v9, v7, v9
	v_mul_i32_i24_e32 v7, 64, v7
	v_sub_u32_e32 v7, v8, v7
	v_lshlrev_b32_e32 v6, 5, v6
	v_ashrrev_i16_sdwa v7, v154, sext(v7) dst_sel:DWORD dst_unused:UNUSED_PAD src0_sel:DWORD src1_sel:BYTE_0
	v_mul_lo_u32 v8, v9, s34
	v_bfe_i32 v7, v7, 0, 16
	v_and_or_b32 v6, v6, 32, v8
	v_add_lshl_u32 v130, v6, v7, 1
	v_add_u32_e32 v6, 0x2000, v5
	v_ashrrev_i32_e32 v7, 31, v6
	v_lshrrev_b32_e32 v7, 22, v7
	v_add_u32_e32 v7, v6, v7
	v_ashrrev_i32_e32 v7, 10, v7
	v_mul_i32_i24_e32 v8, 0x400, v7
	v_sub_u32_e32 v6, v6, v8
	v_lshrrev_b32_e32 v8, 4, v6
	v_bitop3_b32 v6, v8, v6, 32 bitop3:0x6c
	v_ashrrev_i32_e32 v9, 31, v6
	v_lshrrev_b32_e32 v9, 26, v9
	v_lshlrev_b32_e32 v8, 3, v7
	v_add_u32_e32 v9, v6, v9
	v_and_b32_e32 v8, 0x3fffff0, v8
	v_lshrrev_b32_e32 v10, 6, v9
	v_and_b32_e32 v9, 0xc0, v9
	v_add_u32_e32 v8, v10, v8
	v_sub_u32_e32 v6, v6, v9
	v_lshlrev_b32_e32 v7, 5, v7
	v_ashrrev_i16_sdwa v6, v154, sext(v6) dst_sel:DWORD dst_unused:UNUSED_PAD src0_sel:DWORD src1_sel:BYTE_0
	v_mul_lo_u32 v8, v8, s34
	v_bfe_i32 v6, v6, 0, 16
	v_and_or_b32 v7, v7, 32, v8
	v_and_b32_e32 v3, 15, v134
	v_add_lshl_u32 v132, v7, v6, 1
	v_lshlrev_b32_e32 v6, 2, v134
	v_and_b32_e32 v4, 48, v134
	v_lshlrev_b32_e32 v3, 6, v3
	v_and_b32_e32 v6, 32, v6
	v_lshlrev_b32_e32 v11, 6, v134
	v_bitop3_b32 v3, v3, v6, v4 bitop3:0x36
	v_lshlrev_b32_e32 v13, 13, v2
	v_and_or_b32 v2, v11, s40, v4
	v_add_u32_e32 v7, s36, v3
	v_add_u32_e32 v8, s37, v3
	v_add_u32_e32 v9, s38, v3
	v_add_u32_e32 v10, s39, v3
	v_and_b32_e32 v12, 0x3000, v11
	v_add_u32_e32 v3, 0x100, v3
	v_xad_u32 v4, v2, v6, s35
	v_or_b32_e32 v6, 0x800, v13
	v_or_b32_e32 v11, 0x1000, v13
	v_or_b32_e32 v14, 0x1800, v13
	v_mov_b32_e32 v2, 0
	v_add_u32_e32 v145, 0x100, v5
	v_add_u32_e32 v151, s36, v5
	v_add_u32_e32 v153, s37, v5
	v_add_u32_e32 v156, s38, v5
	v_add_u32_e32 v158, s39, v5
	v_mov_b32_e32 v133, v131
	s_mov_b32 s22, -2
	v_add_u32_e32 v144, v7, v12
	v_add_u32_e32 v138, v3, v13
	v_add_u32_e32 v137, v4, v6
	v_add_u32_e32 v136, v4, v11
	v_add_u32_e32 v135, v4, v14
	v_add_u32_e32 v143, 0xc000, v145
	v_add_u32_e32 v142, 0xe000, v145
	v_add_u32_e32 v141, v8, v12
	v_add_u32_e32 v146, 0x2000, v145
	v_add_u32_e32 v140, v9, v12
	v_add_u32_e32 v147, 0x4000, v145
	v_add_u32_e32 v148, 0x6000, v145
	v_add_u32_e32 v139, v10, v12
	v_add_u32_e32 v149, 0x8000, v145
	v_add_u32_e32 v150, 0xa000, v145
	v_add_u32_e32 v152, 0x2000, v151
	v_add_u32_e32 v155, 0x2000, v153
	v_add_u32_e32 v157, 0x2000, v156
	v_add_u32_e32 v159, 0x2000, v158
	v_mov_b32_e32 v3, v2
	v_mov_b32_e32 v4, v2
	v_mov_b32_e32 v5, v2
	v_mov_b32_e32 v6, v2
	v_mov_b32_e32 v7, v2
	v_mov_b32_e32 v8, v2
	v_mov_b32_e32 v9, v2
	v_mov_b32_e32 v10, v2
	v_mov_b32_e32 v11, v2
	v_mov_b32_e32 v12, v2
	v_mov_b32_e32 v13, v2
	v_mov_b32_e32 v14, v2
	v_mov_b32_e32 v15, v2
	v_mov_b32_e32 v16, v2
	v_mov_b32_e32 v17, v2
	v_mov_b32_e32 v18, v2
	v_mov_b32_e32 v19, v2
	v_mov_b32_e32 v20, v2
	v_mov_b32_e32 v21, v2
	v_mov_b32_e32 v22, v2
	v_mov_b32_e32 v23, v2
	v_mov_b32_e32 v24, v2
	v_mov_b32_e32 v25, v2
	v_mov_b32_e32 v26, v2
	v_mov_b32_e32 v27, v2
	v_mov_b32_e32 v28, v2
	v_mov_b32_e32 v29, v2
	v_mov_b32_e32 v30, v2
	v_mov_b32_e32 v31, v2
	v_mov_b32_e32 v32, v2
	v_mov_b32_e32 v33, v2
	v_mov_b32_e32 v34, v2
	v_mov_b32_e32 v35, v2
	v_mov_b32_e32 v36, v2
	v_mov_b32_e32 v37, v2
	v_mov_b32_e32 v38, v2
	v_mov_b32_e32 v39, v2
	v_mov_b32_e32 v40, v2
	v_mov_b32_e32 v41, v2
	v_mov_b32_e32 v42, v2
	v_mov_b32_e32 v43, v2
	v_mov_b32_e32 v44, v2
	v_mov_b32_e32 v45, v2
	v_mov_b32_e32 v46, v2
	v_mov_b32_e32 v47, v2
	v_mov_b32_e32 v48, v2
	v_mov_b32_e32 v49, v2
	v_mov_b32_e32 v50, v2
	v_mov_b32_e32 v51, v2
	v_mov_b32_e32 v52, v2
	v_mov_b32_e32 v53, v2
	v_mov_b32_e32 v54, v2
	v_mov_b32_e32 v55, v2
	v_mov_b32_e32 v56, v2
	v_mov_b32_e32 v57, v2
	v_mov_b32_e32 v58, v2
	v_mov_b32_e32 v59, v2
	v_mov_b32_e32 v60, v2
	v_mov_b32_e32 v61, v2
	v_mov_b32_e32 v62, v2
	v_mov_b32_e32 v63, v2
	v_mov_b32_e32 v64, v2
	v_mov_b32_e32 v65, v2
	v_mov_b32_e32 v66, v2
	v_mov_b32_e32 v67, v2
	v_mov_b32_e32 v68, v2
	v_mov_b32_e32 v69, v2
	v_mov_b32_e32 v70, v2
	v_mov_b32_e32 v71, v2
	v_mov_b32_e32 v72, v2
	v_mov_b32_e32 v73, v2
	v_mov_b32_e32 v74, v2
	v_mov_b32_e32 v75, v2
	v_mov_b32_e32 v76, v2
	v_mov_b32_e32 v77, v2
	v_mov_b32_e32 v78, v2
	v_mov_b32_e32 v79, v2
	v_mov_b32_e32 v80, v2
	v_mov_b32_e32 v81, v2
	v_mov_b32_e32 v82, v2
	v_mov_b32_e32 v83, v2
	v_mov_b32_e32 v84, v2
	v_mov_b32_e32 v85, v2
	v_mov_b32_e32 v86, v2
	v_mov_b32_e32 v87, v2
	v_mov_b32_e32 v88, v2
	v_mov_b32_e32 v89, v2
	v_mov_b32_e32 v90, v2
	v_mov_b32_e32 v91, v2
	v_mov_b32_e32 v92, v2
	v_mov_b32_e32 v93, v2
	v_mov_b32_e32 v94, v2
	v_mov_b32_e32 v95, v2
	v_mov_b32_e32 v96, v2
	v_mov_b32_e32 v97, v2
	v_mov_b32_e32 v98, v2
	v_mov_b32_e32 v99, v2
	v_mov_b32_e32 v100, v2
	v_mov_b32_e32 v101, v2
	v_mov_b32_e32 v102, v2
	v_mov_b32_e32 v103, v2
	v_mov_b32_e32 v104, v2
	v_mov_b32_e32 v105, v2
	v_mov_b32_e32 v106, v2
	v_mov_b32_e32 v107, v2
	v_mov_b32_e32 v108, v2
	v_mov_b32_e32 v109, v2
	v_mov_b32_e32 v110, v2
	v_mov_b32_e32 v111, v2
	v_mov_b32_e32 v112, v2
	v_mov_b32_e32 v113, v2
	v_mov_b32_e32 v114, v2
	v_mov_b32_e32 v115, v2
	v_mov_b32_e32 v116, v2
	v_mov_b32_e32 v117, v2
	v_mov_b32_e32 v118, v2
	v_mov_b32_e32 v119, v2
	v_mov_b32_e32 v120, v2
	v_mov_b32_e32 v121, v2
	v_mov_b32_e32 v122, v2
	v_mov_b32_e32 v123, v2
	v_mov_b32_e32 v124, v2
	v_mov_b32_e32 v125, v2
	v_mov_b32_e32 v126, v2
	v_mov_b32_e32 v127, v2
	v_mov_b32_e32 v128, v2
	v_mov_b32_e32 v129, v2
	s_waitcnt vmcnt(0)
	s_barrier
	s_barrier

; #define GAS __attribute__((address_space(1)))
; __device__ __forceinline__ int otid() { int t = threadIdx.x; asm volatile("" : "+v"(t)); return t; }
; #define WAIT_V(n) asm volatile("s_waitcnt vmcnt(" #n ")" ::: "memory")
; #define BAR __builtin_amdgcn_s_barrier()
; template <int K, int LD = K>
; __device__ __forceinline__ void gemm_main(const GAS bf16* A, const GAS bf16* Bt, int brow, int bcol, f32x4 (&acc)[2][2][4][2]) {
;     ...
;   const int tid_ = otid();
;     ...
;   const int wid = tid_ >> 6, lane = tid_ & 63, wr = wid >> 2, wc = wid & 3, fr = lane & 15, fq = lane >> 4;
; #pragma unroll
;   for (int a = 0; a < 2; ++a)
; #pragma unroll
;     for (int b = 0; b < 2; ++b)
; #pragma unroll
;       for (int m = 0; m < 4; ++m)
; #pragma unroll
;         for (int n = 0; n < 2; ++n) acc[a][b][m][n] = f32x4{0.f, 0.f, 0.f, 0.f};
;   bf16x8 At[4][2], B0[2][2], B1[2][2];
;   unsigned so0, so1;
;   { int r_, c_; stage_rc(tid_ * 16, r_, c_); so0 = (unsigned)(r_ * LD + c_) * 2u; stage_rc(tid_ * 16 + 8192, r_, c_); so1 = (unsigned)(r_ * LD + c_) * 2u; }
;   const GAS char* pA0 = (const GAS char*)A + (long)brow * LD * 2; const GAS char* pA1 = pA0 + (long)HALF * LD * 2;
;   const GAS char* pB0 = (const GAS char*)Bt + (long)bcol * LD * 2; const GAS char* pB1 = pB0 + (long)HALF * LD * 2;
;   asm volatile("" : "+s"(pA0), "+s"(pA1), "+s"(pB0), "+s"(pB1));
;   constexpr int nt = K / BK;
;   static_assert(K % 128 == 0 && K >= 256, "K");
;   if (wr == 1) BAR;
;   WAIT_V(0); BAR;
;   BAR;
.LBB0_345:
	s_or_b64 exec, exec, s[38:39]
	v_bfe_i32 v7, v134, 27, 1
	v_lshlrev_b32_e32 v5, 4, v134
	v_lshrrev_b32_e32 v7, 22, v7
	v_add_u32_e32 v7, v5, v7
	v_and_b32_e32 v7, 0xfffffc00, v7
	v_sub_u32_e32 v7, v5, v7
	v_lshrrev_b32_e32 v8, 4, v7
	v_bitop3_b32 v8, v8, v7, 32 bitop3:0x6c
	v_ashrrev_i32_e32 v7, 31, v7
	v_ashrrev_i32_e32 v6, 31, v134
	v_lshrrev_b32_e32 v7, 26, v7
	v_lshrrev_b32_e32 v6, 26, v6
	v_add_u32_e32 v7, v8, v7
	v_add_u32_e32 v6, v134, v6
	v_ashrrev_i32_e32 v7, 6, v7
	v_ashrrev_i32_e32 v6, 6, v6
	v_mul_i32_i24_e32 v10, 64, v7
	v_lshlrev_b32_e32 v9, 3, v6
	v_lshlrev_b32_e32 v6, 5, v6
	v_sub_u32_e32 v8, v8, v10
	v_and_b32_e32 v9, 0x1ffff0, v9
	v_and_b32_e32 v6, 32, v6
	v_ashrrev_i16_sdwa v8, v144, sext(v8) dst_sel:DWORD dst_unused:UNUSED_PAD src0_sel:DWORD src1_sel:BYTE_0
	v_add_u32_sdwa v6, v6, sext(v8) dst_sel:DWORD dst_unused:UNUSED_PAD src0_sel:DWORD src1_sel:WORD_0
	v_add_lshl_u32 v7, v7, v9, 11
	v_lshl_add_u32 v130, v6, 1, v7
	v_add_u32_e32 v6, 0x2000, v5
	v_ashrrev_i32_e32 v7, 31, v6
	v_lshrrev_b32_e32 v7, 22, v7
	v_add_u32_e32 v7, v6, v7
	v_ashrrev_i32_e32 v7, 10, v7
	v_mul_i32_i24_e32 v8, 0x400, v7
	v_sub_u32_e32 v6, v6, v8
	v_lshrrev_b32_e32 v8, 4, v6
	v_bitop3_b32 v6, v8, v6, 32 bitop3:0x6c
	v_ashrrev_i32_e32 v9, 31, v6
	v_lshrrev_b32_e32 v9, 26, v9
	v_add_u32_e32 v9, v6, v9
	v_lshrrev_b32_e32 v10, 6, v9
	v_and_b32_e32 v9, 0xc0, v9
	v_lshlrev_b32_e32 v8, 3, v7
	v_lshlrev_b32_e32 v7, 5, v7
	v_sub_u32_e32 v6, v6, v9
	v_and_b32_e32 v8, 0x1ffff0, v8
	v_and_b32_e32 v7, 32, v7
	v_ashrrev_i16_sdwa v6, v144, sext(v6) dst_sel:DWORD dst_unused:UNUSED_PAD src0_sel:DWORD src1_sel:BYTE_0
	v_add_u32_sdwa v6, v7, sext(v6) dst_sel:DWORD dst_unused:UNUSED_PAD src0_sel:DWORD src1_sel:WORD_0
	v_add_lshl_u32 v7, v10, v8, 11
	v_and_b32_e32 v3, 15, v134
	v_lshl_add_u32 v132, v6, 1, v7
	v_lshlrev_b32_e32 v6, 2, v134
	v_and_b32_e32 v4, 48, v134
	v_lshlrev_b32_e32 v3, 6, v3
	v_and_b32_e32 v6, 32, v6
	v_lshlrev_b32_e32 v11, 6, v134
	v_bitop3_b32 v3, v3, v6, v4 bitop3:0x36
	v_lshlrev_b32_e32 v13, 13, v2
	v_and_or_b32 v2, v11, s51, v4
	v_add_u32_e32 v7, s42, v3
	v_add_u32_e32 v8, s43, v3
	v_add_u32_e32 v9, s46, v3
	v_add_u32_e32 v10, s47, v3
	v_and_b32_e32 v12, 0x3000, v11
	v_add_u32_e32 v3, 0x100, v3
	v_xad_u32 v4, v2, v6, s48
	v_or_b32_e32 v6, 0x800, v13
	v_or_b32_e32 v11, 0x1000, v13
	v_or_b32_e32 v14, 0x1800, v13
	v_mov_b32_e32 v2, 0
	v_add_u32_e32 v147, 0x100, v5
	v_add_u32_e32 v153, s42, v5
	v_add_u32_e32 v155, s43, v5
	v_add_u32_e32 v157, s46, v5
	v_add_u32_e32 v159, s47, v5
	v_mov_b32_e32 v133, v131
	s_mov_b32 s5, -2
	v_add_u32_e32 v146, v7, v12
	v_add_u32_e32 v138, v3, v13
	v_add_u32_e32 v137, v4, v6
	v_add_u32_e32 v136, v4, v11
	v_add_u32_e32 v135, v4, v14
	v_add_u32_e32 v143, 0xc000, v147
	v_add_u32_e32 v142, 0xe000, v147
	v_add_u32_e32 v141, v8, v12
	v_add_u32_e32 v148, 0x2000, v147
	v_add_u32_e32 v140, v9, v12
	v_add_u32_e32 v149, 0x4000, v147
	v_add_u32_e32 v150, 0x6000, v147
	v_add_u32_e32 v139, v10, v12
	v_add_u32_e32 v151, 0x8000, v147
	v_add_u32_e32 v152, 0xa000, v147
	v_add_u32_e32 v154, 0x2000, v153
	v_add_u32_e32 v156, 0x2000, v155
	v_add_u32_e32 v158, 0x2000, v157
	v_add_u32_e32 v160, 0x2000, v159
	v_mov_b32_e32 v3, v2
	v_mov_b32_e32 v4, v2
	v_mov_b32_e32 v5, v2
	v_mov_b32_e32 v6, v2
	v_mov_b32_e32 v7, v2
	v_mov_b32_e32 v8, v2
	v_mov_b32_e32 v9, v2
	v_mov_b32_e32 v10, v2
	v_mov_b32_e32 v11, v2
	v_mov_b32_e32 v12, v2
	v_mov_b32_e32 v13, v2
	v_mov_b32_e32 v14, v2
	v_mov_b32_e32 v15, v2
	v_mov_b32_e32 v16, v2
	v_mov_b32_e32 v17, v2
	v_mov_b32_e32 v18, v2
	v_mov_b32_e32 v19, v2
	v_mov_b32_e32 v20, v2
	v_mov_b32_e32 v21, v2
	v_mov_b32_e32 v22, v2
	v_mov_b32_e32 v23, v2
	v_mov_b32_e32 v24, v2
	v_mov_b32_e32 v25, v2
	v_mov_b32_e32 v26, v2
	v_mov_b32_e32 v27, v2
	v_mov_b32_e32 v28, v2
	v_mov_b32_e32 v29, v2
	v_mov_b32_e32 v30, v2
	v_mov_b32_e32 v31, v2
	v_mov_b32_e32 v32, v2
	v_mov_b32_e32 v33, v2
	v_mov_b32_e32 v34, v2
	v_mov_b32_e32 v35, v2
	v_mov_b32_e32 v36, v2
	v_mov_b32_e32 v37, v2
	v_mov_b32_e32 v38, v2
	v_mov_b32_e32 v39, v2
	v_mov_b32_e32 v40, v2
	v_mov_b32_e32 v41, v2
	v_mov_b32_e32 v42, v2
	v_mov_b32_e32 v43, v2
	v_mov_b32_e32 v44, v2
	v_mov_b32_e32 v45, v2
	v_mov_b32_e32 v46, v2
	v_mov_b32_e32 v47, v2
	v_mov_b32_e32 v48, v2
	v_mov_b32_e32 v49, v2
	v_mov_b32_e32 v50, v2
	v_mov_b32_e32 v51, v2
	v_mov_b32_e32 v52, v2
	v_mov_b32_e32 v53, v2
	v_mov_b32_e32 v54, v2
	v_mov_b32_e32 v55, v2
	v_mov_b32_e32 v56, v2
	v_mov_b32_e32 v57, v2
	v_mov_b32_e32 v58, v2
	v_mov_b32_e32 v59, v2
	v_mov_b32_e32 v60, v2
	v_mov_b32_e32 v61, v2
	v_mov_b32_e32 v62, v2
	v_mov_b32_e32 v63, v2
	v_mov_b32_e32 v64, v2
	v_mov_b32_e32 v65, v2
	v_mov_b32_e32 v66, v2
	v_mov_b32_e32 v67, v2
	v_mov_b32_e32 v68, v2
	v_mov_b32_e32 v69, v2
	v_mov_b32_e32 v70, v2
	v_mov_b32_e32 v71, v2
	v_mov_b32_e32 v72, v2
	v_mov_b32_e32 v73, v2
	v_mov_b32_e32 v74, v2
	v_mov_b32_e32 v75, v2
	v_mov_b32_e32 v76, v2
	v_mov_b32_e32 v77, v2
	v_mov_b32_e32 v78, v2
	v_mov_b32_e32 v79, v2
	v_mov_b32_e32 v80, v2
	v_mov_b32_e32 v81, v2
	v_mov_b32_e32 v82, v2
	v_mov_b32_e32 v83, v2
	v_mov_b32_e32 v84, v2
	v_mov_b32_e32 v85, v2
	v_mov_b32_e32 v86, v2
	v_mov_b32_e32 v87, v2
	v_mov_b32_e32 v88, v2
	v_mov_b32_e32 v89, v2
	v_mov_b32_e32 v90, v2
	v_mov_b32_e32 v91, v2
	v_mov_b32_e32 v92, v2
	v_mov_b32_e32 v93, v2
	v_mov_b32_e32 v94, v2
	v_mov_b32_e32 v95, v2
	v_mov_b32_e32 v96, v2
	v_mov_b32_e32 v97, v2
	v_mov_b32_e32 v98, v2
	v_mov_b32_e32 v99, v2
	v_mov_b32_e32 v100, v2
	v_mov_b32_e32 v101, v2
	v_mov_b32_e32 v102, v2
	v_mov_b32_e32 v103, v2
	v_mov_b32_e32 v104, v2
	v_mov_b32_e32 v105, v2
	v_mov_b32_e32 v106, v2
	v_mov_b32_e32 v107, v2
	v_mov_b32_e32 v108, v2
	v_mov_b32_e32 v109, v2
	v_mov_b32_e32 v110, v2
	v_mov_b32_e32 v111, v2
	v_mov_b32_e32 v112, v2
	v_mov_b32_e32 v113, v2
	v_mov_b32_e32 v114, v2
	v_mov_b32_e32 v115, v2
	v_mov_b32_e32 v116, v2
	v_mov_b32_e32 v117, v2
	v_mov_b32_e32 v118, v2
	v_mov_b32_e32 v119, v2
	v_mov_b32_e32 v120, v2
	v_mov_b32_e32 v121, v2
	v_mov_b32_e32 v122, v2
	v_mov_b32_e32 v123, v2
	v_mov_b32_e32 v124, v2
	v_mov_b32_e32 v125, v2
	v_mov_b32_e32 v126, v2
	v_mov_b32_e32 v127, v2
	v_mov_b32_e32 v128, v2
	v_mov_b32_e32 v129, v2
	s_waitcnt vmcnt(0)
	s_barrier
	s_barrier

; #define GAS __attribute__((address_space(1)))
; __device__ __forceinline__ int otid() { int t = threadIdx.x; asm volatile("" : "+v"(t)); return t; }
; #define WAIT_V(n) asm volatile("s_waitcnt vmcnt(" #n ")" ::: "memory")
; #define BAR __builtin_amdgcn_s_barrier()
; template <int K, int LD = K>
; __device__ __forceinline__ void gemm_main(const GAS bf16* A, const GAS bf16* Bt, int brow, int bcol, f32x4 (&acc)[2][2][4][2]) {
;     ...
;   const int tid_ = otid();
;     ...
;   const int wid = tid_ >> 6, lane = tid_ & 63, wr = wid >> 2, wc = wid & 3, fr = lane & 15, fq = lane >> 4;
; #pragma unroll
;   for (int a = 0; a < 2; ++a)
; #pragma unroll
;     for (int b = 0; b < 2; ++b)
; #pragma unroll
;       for (int m = 0; m < 4; ++m)
; #pragma unroll
;         for (int n = 0; n < 2; ++n) acc[a][b][m][n] = f32x4{0.f, 0.f, 0.f, 0.f};
;   bf16x8 At[4][2], B0[2][2], B1[2][2];
;   unsigned so0, so1;
;   { int r_, c_; stage_rc(tid_ * 16, r_, c_); so0 = (unsigned)(r_ * LD + c_) * 2u; stage_rc(tid_ * 16 + 8192, r_, c_); so1 = (unsigned)(r_ * LD + c_) * 2u; }
;   const GAS char* pA0 = (const GAS char*)A + (long)brow * LD * 2; const GAS char* pA1 = pA0 + (long)HALF * LD * 2;
;   const GAS char* pB0 = (const GAS char*)Bt + (long)bcol * LD * 2; const GAS char* pB1 = pB0 + (long)HALF * LD * 2;
;   asm volatile("" : "+s"(pA0), "+s"(pA1), "+s"(pB0), "+s"(pB1));
;   constexpr int nt = K / BK;
;   static_assert(K % 128 == 0 && K >= 256, "K");
;   if (wr == 1) BAR;
;   WAIT_V(0); BAR;
;   BAR;
.LBB0_708:
	s_or_b64 exec, exec, s[30:31]
	v_bfe_i32 v6, v134, 27, 1
	v_lshlrev_b32_e32 v141, 4, v134
	v_lshrrev_b32_e32 v6, 22, v6
	v_add_u32_e32 v6, v141, v6
	v_and_b32_e32 v6, 0xfffffc00, v6
	v_sub_u32_e32 v6, v141, v6
	v_lshrrev_b32_e32 v7, 4, v6
	v_bitop3_b32 v7, v7, v6, 32 bitop3:0x6c
	v_ashrrev_i32_e32 v6, 31, v6
	v_ashrrev_i32_e32 v5, 31, v134
	v_lshrrev_b32_e32 v6, 26, v6
	v_lshrrev_b32_e32 v5, 26, v5
	v_add_u32_e32 v6, v7, v6
	v_add_u32_e32 v5, v134, v5
	v_ashrrev_i32_e32 v6, 6, v6
	v_ashrrev_i32_e32 v5, 6, v5
	v_mul_i32_i24_e32 v9, 64, v6
	v_lshlrev_b32_e32 v8, 3, v5
	v_lshlrev_b32_e32 v5, 5, v5
	v_sub_u32_e32 v7, v7, v9
	v_and_b32_e32 v8, 0x3ffff0, v8
	v_and_b32_e32 v5, 32, v5
	v_ashrrev_i16_sdwa v7, v1, sext(v7) dst_sel:DWORD dst_unused:UNUSED_PAD src0_sel:DWORD src1_sel:BYTE_0
	v_add_u32_sdwa v5, v5, sext(v7) dst_sel:DWORD dst_unused:UNUSED_PAD src0_sel:DWORD src1_sel:WORD_0
	v_add_lshl_u32 v6, v6, v8, 10
	v_lshl_add_u32 v130, v5, 1, v6
	v_add_u32_e32 v5, 0x2000, v141
	v_ashrrev_i32_e32 v6, 31, v5
	v_lshrrev_b32_e32 v6, 22, v6
	v_add_u32_e32 v6, v5, v6
	v_ashrrev_i32_e32 v6, 10, v6
	v_mul_i32_i24_e32 v7, 0x400, v6
	v_sub_u32_e32 v5, v5, v7
	v_lshrrev_b32_e32 v7, 4, v5
	v_bitop3_b32 v5, v7, v5, 32 bitop3:0x6c
	v_ashrrev_i32_e32 v8, 31, v5
	v_lshrrev_b32_e32 v8, 26, v8
	v_add_u32_e32 v8, v5, v8
	v_lshrrev_b32_e32 v9, 6, v8
	v_and_b32_e32 v8, 0xc0, v8
	v_lshlrev_b32_e32 v7, 3, v6
	v_lshlrev_b32_e32 v6, 5, v6
	v_sub_u32_e32 v5, v5, v8
	v_and_b32_e32 v7, 0x3ffff0, v7
	v_and_b32_e32 v6, 32, v6
	v_ashrrev_i16_sdwa v5, v1, sext(v5) dst_sel:DWORD dst_unused:UNUSED_PAD src0_sel:DWORD src1_sel:BYTE_0
	v_add_u32_sdwa v5, v6, sext(v5) dst_sel:DWORD dst_unused:UNUSED_PAD src0_sel:DWORD src1_sel:WORD_0
	v_add_lshl_u32 v6, v9, v7, 10
	v_and_b32_e32 v3, 15, v134
	v_lshl_add_u32 v132, v5, 1, v6
	v_lshlrev_b32_e32 v5, 2, v134
	v_and_b32_e32 v4, 48, v134
	v_lshlrev_b32_e32 v3, 6, v3
	v_and_b32_e32 v5, 32, v5
	v_lshlrev_b32_e32 v10, 6, v134
	v_bitop3_b32 v3, v3, v5, v4 bitop3:0x36
	v_lshlrev_b32_e32 v12, 13, v2
	v_and_or_b32 v2, v10, s54, v4
	v_add_u32_e32 v6, s47, v3
	v_add_u32_e32 v7, s48, v3
	v_add_u32_e32 v8, s49, v3
	v_add_u32_e32 v9, s50, v3
	v_and_b32_e32 v11, 0x3000, v10
	v_add_u32_e32 v3, 0x100, v3
	v_xad_u32 v4, v2, v5, s51
	v_or_b32_e32 v5, 0x800, v12
	v_or_b32_e32 v10, 0x1000, v12
	v_or_b32_e32 v13, 0x1800, v12
	v_mov_b32_e32 v2, 0
	v_mov_b32_e32 v133, v131
	s_mov_b32 s17, -2
	v_add_u32_e32 v143, v6, v11
	v_add_u32_e32 v138, v3, v12
	v_add_u32_e32 v137, v4, v5
	v_add_u32_e32 v136, v4, v10
	v_add_u32_e32 v135, v4, v13
	v_add_u32_e32 v142, v7, v11
	v_add_u32_e32 v140, v8, v11
	v_add_u32_e32 v139, v9, v11
	v_mov_b32_e32 v3, v2
	v_mov_b32_e32 v4, v2
	v_mov_b32_e32 v5, v2
	v_mov_b32_e32 v6, v2
	v_mov_b32_e32 v7, v2
	v_mov_b32_e32 v8, v2
	v_mov_b32_e32 v9, v2
	v_mov_b32_e32 v10, v2
	v_mov_b32_e32 v11, v2
	v_mov_b32_e32 v12, v2
	v_mov_b32_e32 v13, v2
	v_mov_b32_e32 v14, v2
	v_mov_b32_e32 v15, v2
	v_mov_b32_e32 v16, v2
	v_mov_b32_e32 v17, v2
	v_mov_b32_e32 v18, v2
	v_mov_b32_e32 v19, v2
	v_mov_b32_e32 v20, v2
	v_mov_b32_e32 v21, v2
	v_mov_b32_e32 v22, v2
	v_mov_b32_e32 v23, v2
	v_mov_b32_e32 v24, v2
	v_mov_b32_e32 v25, v2
	v_mov_b32_e32 v26, v2
	v_mov_b32_e32 v27, v2
	v_mov_b32_e32 v28, v2
	v_mov_b32_e32 v29, v2
	v_mov_b32_e32 v30, v2
	v_mov_b32_e32 v31, v2
	v_mov_b32_e32 v32, v2
	v_mov_b32_e32 v33, v2
	v_mov_b32_e32 v34, v2
	v_mov_b32_e32 v35, v2
	v_mov_b32_e32 v36, v2
	v_mov_b32_e32 v37, v2
	v_mov_b32_e32 v38, v2
	v_mov_b32_e32 v39, v2
	v_mov_b32_e32 v40, v2
	v_mov_b32_e32 v41, v2
	v_mov_b32_e32 v42, v2
	v_mov_b32_e32 v43, v2
	v_mov_b32_e32 v44, v2
	v_mov_b32_e32 v45, v2
	v_mov_b32_e32 v46, v2
	v_mov_b32_e32 v47, v2
	v_mov_b32_e32 v48, v2
	v_mov_b32_e32 v49, v2
	v_mov_b32_e32 v50, v2
	v_mov_b32_e32 v51, v2
	v_mov_b32_e32 v52, v2
	v_mov_b32_e32 v53, v2
	v_mov_b32_e32 v54, v2
	v_mov_b32_e32 v55, v2
	v_mov_b32_e32 v56, v2
	v_mov_b32_e32 v57, v2
	v_mov_b32_e32 v58, v2
	v_mov_b32_e32 v59, v2
	v_mov_b32_e32 v60, v2
	v_mov_b32_e32 v61, v2
	v_mov_b32_e32 v62, v2
	v_mov_b32_e32 v63, v2
	v_mov_b32_e32 v64, v2
	v_mov_b32_e32 v65, v2
	v_mov_b32_e32 v66, v2
	v_mov_b32_e32 v67, v2
	v_mov_b32_e32 v68, v2
	v_mov_b32_e32 v69, v2
	v_mov_b32_e32 v70, v2
	v_mov_b32_e32 v71, v2
	v_mov_b32_e32 v72, v2
	v_mov_b32_e32 v73, v2
	v_mov_b32_e32 v74, v2
	v_mov_b32_e32 v75, v2
	v_mov_b32_e32 v76, v2
	v_mov_b32_e32 v77, v2
	v_mov_b32_e32 v78, v2
	v_mov_b32_e32 v79, v2
	v_mov_b32_e32 v80, v2
	v_mov_b32_e32 v81, v2
	v_mov_b32_e32 v82, v2
	v_mov_b32_e32 v83, v2
	v_mov_b32_e32 v84, v2
	v_mov_b32_e32 v85, v2
	v_mov_b32_e32 v86, v2
	v_mov_b32_e32 v87, v2
	v_mov_b32_e32 v88, v2
	v_mov_b32_e32 v89, v2
	v_mov_b32_e32 v90, v2
	v_mov_b32_e32 v91, v2
	v_mov_b32_e32 v92, v2
	v_mov_b32_e32 v93, v2
	v_mov_b32_e32 v94, v2
	v_mov_b32_e32 v95, v2
	v_mov_b32_e32 v96, v2
	v_mov_b32_e32 v97, v2
	v_mov_b32_e32 v98, v2
	v_mov_b32_e32 v99, v2
	v_mov_b32_e32 v100, v2
	v_mov_b32_e32 v101, v2
	v_mov_b32_e32 v102, v2
	v_mov_b32_e32 v103, v2
	v_mov_b32_e32 v104, v2
	v_mov_b32_e32 v105, v2
	v_mov_b32_e32 v106, v2
	v_mov_b32_e32 v107, v2
	v_mov_b32_e32 v108, v2
	v_mov_b32_e32 v109, v2
	v_mov_b32_e32 v110, v2
	v_mov_b32_e32 v111, v2
	v_mov_b32_e32 v112, v2
	v_mov_b32_e32 v113, v2
	v_mov_b32_e32 v114, v2
	v_mov_b32_e32 v115, v2
	v_mov_b32_e32 v116, v2
	v_mov_b32_e32 v117, v2
	v_mov_b32_e32 v118, v2
	v_mov_b32_e32 v119, v2
	v_mov_b32_e32 v120, v2
	v_mov_b32_e32 v121, v2
	v_mov_b32_e32 v122, v2
	v_mov_b32_e32 v123, v2
	v_mov_b32_e32 v124, v2
	v_mov_b32_e32 v125, v2
	v_mov_b32_e32 v126, v2
	v_mov_b32_e32 v127, v2
	v_mov_b32_e32 v128, v2
	v_mov_b32_e32 v129, v2
	s_waitcnt vmcnt(0)
	s_barrier
	s_barrier

; #define GAS __attribute__((address_space(1)))
; __device__ __forceinline__ int otid() { int t = threadIdx.x; asm volatile("" : "+v"(t)); return t; }
; #define WAIT_V(n) asm volatile("s_waitcnt vmcnt(" #n ")" ::: "memory")
; #define BAR __builtin_amdgcn_s_barrier()
; template <int K, int LD = K>
; __device__ __forceinline__ void gemm_main(const GAS bf16* A, const GAS bf16* Bt, int brow, int bcol, f32x4 (&acc)[2][2][4][2]) {
;     ...
;   const int tid_ = otid();
;     ...
;   const int wid = tid_ >> 6, lane = tid_ & 63, wr = wid >> 2, wc = wid & 3, fr = lane & 15, fq = lane >> 4;
; #pragma unroll
;   for (int a = 0; a < 2; ++a)
; #pragma unroll
;     for (int b = 0; b < 2; ++b)
; #pragma unroll
;       for (int m = 0; m < 4; ++m)
; #pragma unroll
;         for (int n = 0; n < 2; ++n) acc[a][b][m][n] = f32x4{0.f, 0.f, 0.f, 0.f};
;   bf16x8 At[4][2], B0[2][2], B1[2][2];
;   unsigned so0, so1;
;   { int r_, c_; stage_rc(tid_ * 16, r_, c_); so0 = (unsigned)(r_ * LD + c_) * 2u; stage_rc(tid_ * 16 + 8192, r_, c_); so1 = (unsigned)(r_ * LD + c_) * 2u; }
;   const GAS char* pA0 = (const GAS char*)A + (long)brow * LD * 2; const GAS char* pA1 = pA0 + (long)HALF * LD * 2;
;   const GAS char* pB0 = (const GAS char*)Bt + (long)bcol * LD * 2; const GAS char* pB1 = pB0 + (long)HALF * LD * 2;
;   asm volatile("" : "+s"(pA0), "+s"(pA1), "+s"(pB0), "+s"(pB1));
;   constexpr int nt = K / BK;
;   static_assert(K % 128 == 0 && K >= 256, "K");
;   if (wr == 1) BAR;
;   WAIT_V(0); BAR;
;   BAR;
.LBB0_714:
	s_or_b64 exec, exec, s[28:29]
	v_bfe_i32 v6, v134, 27, 1
	v_lshlrev_b32_e32 v141, 4, v134
	v_lshrrev_b32_e32 v6, 22, v6
	v_add_u32_e32 v6, v141, v6
	v_and_b32_e32 v6, 0xfffffc00, v6
	v_sub_u32_e32 v6, v141, v6
	v_lshrrev_b32_e32 v7, 4, v6
	v_bitop3_b32 v7, v7, v6, 32 bitop3:0x6c
	v_ashrrev_i32_e32 v6, 31, v6
	v_ashrrev_i32_e32 v5, 31, v134
	v_lshrrev_b32_e32 v6, 26, v6
	v_lshrrev_b32_e32 v5, 26, v5
	v_add_u32_e32 v6, v7, v6
	v_add_u32_e32 v5, v134, v5
	v_ashrrev_i32_e32 v6, 6, v6
	v_ashrrev_i32_e32 v5, 6, v5
	v_mul_i32_i24_e32 v9, 64, v6
	v_lshlrev_b32_e32 v8, 3, v5
	v_lshlrev_b32_e32 v5, 5, v5
	v_sub_u32_e32 v7, v7, v9
	v_and_b32_e32 v8, 0x3ffff0, v8
	v_and_b32_e32 v5, 32, v5
	v_ashrrev_i16_sdwa v7, v1, sext(v7) dst_sel:DWORD dst_unused:UNUSED_PAD src0_sel:DWORD src1_sel:BYTE_0
	v_add_u32_sdwa v5, v5, sext(v7) dst_sel:DWORD dst_unused:UNUSED_PAD src0_sel:DWORD src1_sel:WORD_0
	v_add_lshl_u32 v6, v6, v8, 10
	v_lshl_add_u32 v130, v5, 1, v6
	v_add_u32_e32 v5, 0x2000, v141
	v_ashrrev_i32_e32 v6, 31, v5
	v_lshrrev_b32_e32 v6, 22, v6
	v_add_u32_e32 v6, v5, v6
	v_ashrrev_i32_e32 v6, 10, v6
	v_mul_i32_i24_e32 v7, 0x400, v6
	v_sub_u32_e32 v5, v5, v7
	v_lshrrev_b32_e32 v7, 4, v5
	v_bitop3_b32 v5, v7, v5, 32 bitop3:0x6c
	v_ashrrev_i32_e32 v8, 31, v5
	v_lshrrev_b32_e32 v8, 26, v8
	v_add_u32_e32 v8, v5, v8
	v_lshrrev_b32_e32 v9, 6, v8
	v_and_b32_e32 v8, 0xc0, v8
	v_lshlrev_b32_e32 v7, 3, v6
	v_lshlrev_b32_e32 v6, 5, v6
	v_sub_u32_e32 v5, v5, v8
	v_and_b32_e32 v7, 0x3ffff0, v7
	v_and_b32_e32 v6, 32, v6
	v_ashrrev_i16_sdwa v5, v1, sext(v5) dst_sel:DWORD dst_unused:UNUSED_PAD src0_sel:DWORD src1_sel:BYTE_0
	v_add_u32_sdwa v5, v6, sext(v5) dst_sel:DWORD dst_unused:UNUSED_PAD src0_sel:DWORD src1_sel:WORD_0
	v_add_lshl_u32 v6, v9, v7, 10
	v_and_b32_e32 v3, 15, v134
	v_lshl_add_u32 v132, v5, 1, v6
	v_lshlrev_b32_e32 v5, 2, v134
	v_and_b32_e32 v4, 48, v134
	v_lshlrev_b32_e32 v3, 6, v3
	v_and_b32_e32 v5, 32, v5
	v_lshlrev_b32_e32 v10, 6, v134
	v_bitop3_b32 v3, v3, v5, v4 bitop3:0x36
	v_lshlrev_b32_e32 v12, 13, v2
	v_and_or_b32 v2, v10, s54, v4
	v_add_u32_e32 v6, s47, v3
	v_add_u32_e32 v7, s48, v3
	v_add_u32_e32 v8, s49, v3
	v_add_u32_e32 v9, s50, v3
	v_and_b32_e32 v11, 0x3000, v10
	v_add_u32_e32 v3, 0x100, v3
	v_xad_u32 v4, v2, v5, s51
	v_or_b32_e32 v5, 0x800, v12
	v_or_b32_e32 v10, 0x1000, v12
	v_or_b32_e32 v13, 0x1800, v12
	v_mov_b32_e32 v2, 0
	v_mov_b32_e32 v133, v131
	s_mov_b32 s17, -2
	v_add_u32_e32 v143, v6, v11
	v_add_u32_e32 v138, v3, v12
	v_add_u32_e32 v137, v4, v5
	v_add_u32_e32 v136, v4, v10
	v_add_u32_e32 v135, v4, v13
	v_add_u32_e32 v142, v7, v11
	v_add_u32_e32 v140, v8, v11
	v_add_u32_e32 v139, v9, v11
	v_mov_b32_e32 v3, v2
	v_mov_b32_e32 v4, v2
	v_mov_b32_e32 v5, v2
	v_mov_b32_e32 v6, v2
	v_mov_b32_e32 v7, v2
	v_mov_b32_e32 v8, v2
	v_mov_b32_e32 v9, v2
	v_mov_b32_e32 v10, v2
	v_mov_b32_e32 v11, v2
	v_mov_b32_e32 v12, v2
	v_mov_b32_e32 v13, v2
	v_mov_b32_e32 v14, v2
	v_mov_b32_e32 v15, v2
	v_mov_b32_e32 v16, v2
	v_mov_b32_e32 v17, v2
	v_mov_b32_e32 v18, v2
	v_mov_b32_e32 v19, v2
	v_mov_b32_e32 v20, v2
	v_mov_b32_e32 v21, v2
	v_mov_b32_e32 v22, v2
	v_mov_b32_e32 v23, v2
	v_mov_b32_e32 v24, v2
	v_mov_b32_e32 v25, v2
	v_mov_b32_e32 v26, v2
	v_mov_b32_e32 v27, v2
	v_mov_b32_e32 v28, v2
	v_mov_b32_e32 v29, v2
	v_mov_b32_e32 v30, v2
	v_mov_b32_e32 v31, v2
	v_mov_b32_e32 v32, v2
	v_mov_b32_e32 v33, v2
	v_mov_b32_e32 v34, v2
	v_mov_b32_e32 v35, v2
	v_mov_b32_e32 v36, v2
	v_mov_b32_e32 v37, v2
	v_mov_b32_e32 v38, v2
	v_mov_b32_e32 v39, v2
	v_mov_b32_e32 v40, v2
	v_mov_b32_e32 v41, v2
	v_mov_b32_e32 v42, v2
	v_mov_b32_e32 v43, v2
	v_mov_b32_e32 v44, v2
	v_mov_b32_e32 v45, v2
	v_mov_b32_e32 v46, v2
	v_mov_b32_e32 v47, v2
	v_mov_b32_e32 v48, v2
	v_mov_b32_e32 v49, v2
	v_mov_b32_e32 v50, v2
	v_mov_b32_e32 v51, v2
	v_mov_b32_e32 v52, v2
	v_mov_b32_e32 v53, v2
	v_mov_b32_e32 v54, v2
	v_mov_b32_e32 v55, v2
	v_mov_b32_e32 v56, v2
	v_mov_b32_e32 v57, v2
	v_mov_b32_e32 v58, v2
	v_mov_b32_e32 v59, v2
	v_mov_b32_e32 v60, v2
	v_mov_b32_e32 v61, v2
	v_mov_b32_e32 v62, v2
	v_mov_b32_e32 v63, v2
	v_mov_b32_e32 v64, v2
	v_mov_b32_e32 v65, v2
	v_mov_b32_e32 v66, v2
	v_mov_b32_e32 v67, v2
	v_mov_b32_e32 v68, v2
	v_mov_b32_e32 v69, v2
	v_mov_b32_e32 v70, v2
	v_mov_b32_e32 v71, v2
	v_mov_b32_e32 v72, v2
	v_mov_b32_e32 v73, v2
	v_mov_b32_e32 v74, v2
	v_mov_b32_e32 v75, v2
	v_mov_b32_e32 v76, v2
	v_mov_b32_e32 v77, v2
	v_mov_b32_e32 v78, v2
	v_mov_b32_e32 v79, v2
	v_mov_b32_e32 v80, v2
	v_mov_b32_e32 v81, v2
	v_mov_b32_e32 v82, v2
	v_mov_b32_e32 v83, v2
	v_mov_b32_e32 v84, v2
	v_mov_b32_e32 v85, v2
	v_mov_b32_e32 v86, v2
	v_mov_b32_e32 v87, v2
	v_mov_b32_e32 v88, v2
	v_mov_b32_e32 v89, v2
	v_mov_b32_e32 v90, v2
	v_mov_b32_e32 v91, v2
	v_mov_b32_e32 v92, v2
	v_mov_b32_e32 v93, v2
	v_mov_b32_e32 v94, v2
	v_mov_b32_e32 v95, v2
	v_mov_b32_e32 v96, v2
	v_mov_b32_e32 v97, v2
	v_mov_b32_e32 v98, v2
	v_mov_b32_e32 v99, v2
	v_mov_b32_e32 v100, v2
	v_mov_b32_e32 v101, v2
	v_mov_b32_e32 v102, v2
	v_mov_b32_e32 v103, v2
	v_mov_b32_e32 v104, v2
	v_mov_b32_e32 v105, v2
	v_mov_b32_e32 v106, v2
	v_mov_b32_e32 v107, v2
	v_mov_b32_e32 v108, v2
	v_mov_b32_e32 v109, v2
	v_mov_b32_e32 v110, v2
	v_mov_b32_e32 v111, v2
	v_mov_b32_e32 v112, v2
	v_mov_b32_e32 v113, v2
	v_mov_b32_e32 v114, v2
	v_mov_b32_e32 v115, v2
	v_mov_b32_e32 v116, v2
	v_mov_b32_e32 v117, v2
	v_mov_b32_e32 v118, v2
	v_mov_b32_e32 v119, v2
	v_mov_b32_e32 v120, v2
	v_mov_b32_e32 v121, v2
	v_mov_b32_e32 v122, v2
	v_mov_b32_e32 v123, v2
	v_mov_b32_e32 v124, v2
	v_mov_b32_e32 v125, v2
	v_mov_b32_e32 v126, v2
	v_mov_b32_e32 v127, v2
	v_mov_b32_e32 v128, v2
	v_mov_b32_e32 v129, v2
	s_waitcnt vmcnt(0)
	s_barrier
	s_barrier

; #define GAS __attribute__((address_space(1)))
; __device__ __forceinline__ int otid() { int t = threadIdx.x; asm volatile("" : "+v"(t)); return t; }
; #define WAIT_V(n) asm volatile("s_waitcnt vmcnt(" #n ")" ::: "memory")
; #define BAR __builtin_amdgcn_s_barrier()
; template <int K, int LD = K>
; __device__ __forceinline__ void gemm_main(const GAS bf16* A, const GAS bf16* Bt, int brow, int bcol, f32x4 (&acc)[2][2][4][2]) {
;     ...
;   const int tid_ = otid();
;     ...
;   const int wid = tid_ >> 6, lane = tid_ & 63, wr = wid >> 2, wc = wid & 3, fr = lane & 15, fq = lane >> 4;
; #pragma unroll
;   for (int a = 0; a < 2; ++a)
; #pragma unroll
;     for (int b = 0; b < 2; ++b)
; #pragma unroll
;       for (int m = 0; m < 4; ++m)
; #pragma unroll
;         for (int n = 0; n < 2; ++n) acc[a][b][m][n] = f32x4{0.f, 0.f, 0.f, 0.f};
;   bf16x8 At[4][2], B0[2][2], B1[2][2];
;   unsigned so0, so1;
;   { int r_, c_; stage_rc(tid_ * 16, r_, c_); so0 = (unsigned)(r_ * LD + c_) * 2u; stage_rc(tid_ * 16 + 8192, r_, c_); so1 = (unsigned)(r_ * LD + c_) * 2u; }
;   const GAS char* pA0 = (const GAS char*)A + (long)brow * LD * 2; const GAS char* pA1 = pA0 + (long)HALF * LD * 2;
;   const GAS char* pB0 = (const GAS char*)Bt + (long)bcol * LD * 2; const GAS char* pB1 = pB0 + (long)HALF * LD * 2;
;   asm volatile("" : "+s"(pA0), "+s"(pA1), "+s"(pB0), "+s"(pB1));
;   constexpr int nt = K / BK;
;   static_assert(K % 128 == 0 && K >= 256, "K");
;   if (wr == 1) BAR;
;   WAIT_V(0); BAR;
;   BAR;
.LBB0_766:
	s_or_b64 exec, exec, s[22:23]
	v_bfe_i32 v7, v134, 27, 1
	v_lshlrev_b32_e32 v5, 4, v134
	v_lshrrev_b32_e32 v7, 22, v7
	v_add_u32_e32 v7, v5, v7
	v_and_b32_e32 v7, 0xfffffc00, v7
	v_sub_u32_e32 v7, v5, v7
	v_lshrrev_b32_e32 v8, 4, v7
	v_bitop3_b32 v8, v8, v7, 32 bitop3:0x6c
	v_ashrrev_i32_e32 v7, 31, v7
	v_ashrrev_i32_e32 v6, 31, v134
	v_lshrrev_b32_e32 v7, 26, v7
	v_lshrrev_b32_e32 v6, 26, v6
	v_add_u32_e32 v7, v8, v7
	v_add_u32_e32 v6, v134, v6
	v_ashrrev_i32_e32 v7, 6, v7
	v_ashrrev_i32_e32 v6, 6, v6
	v_mul_i32_i24_e32 v10, 64, v7
	v_lshlrev_b32_e32 v9, 3, v6
	v_lshlrev_b32_e32 v6, 5, v6
	v_sub_u32_e32 v8, v8, v10
	v_and_b32_e32 v9, 0x1ffff0, v9
	v_and_b32_e32 v6, 32, v6
	v_ashrrev_i16_sdwa v8, v1, sext(v8) dst_sel:DWORD dst_unused:UNUSED_PAD src0_sel:DWORD src1_sel:BYTE_0
	v_add_u32_sdwa v6, v6, sext(v8) dst_sel:DWORD dst_unused:UNUSED_PAD src0_sel:DWORD src1_sel:WORD_0
	v_add_lshl_u32 v7, v7, v9, 11
	v_lshl_add_u32 v130, v6, 1, v7
	v_add_u32_e32 v6, 0x2000, v5
	v_ashrrev_i32_e32 v7, 31, v6
	v_lshrrev_b32_e32 v7, 22, v7
	v_add_u32_e32 v7, v6, v7
	v_ashrrev_i32_e32 v7, 10, v7
	v_mul_i32_i24_e32 v8, 0x400, v7
	v_sub_u32_e32 v6, v6, v8
	v_lshrrev_b32_e32 v8, 4, v6
	v_bitop3_b32 v6, v8, v6, 32 bitop3:0x6c
	v_ashrrev_i32_e32 v9, 31, v6
	v_lshrrev_b32_e32 v9, 26, v9
	v_add_u32_e32 v9, v6, v9
	v_lshrrev_b32_e32 v10, 6, v9
	v_and_b32_e32 v9, 0xc0, v9
	v_lshlrev_b32_e32 v8, 3, v7
	v_lshlrev_b32_e32 v7, 5, v7
	v_sub_u32_e32 v6, v6, v9
	v_and_b32_e32 v8, 0x1ffff0, v8
	v_and_b32_e32 v7, 32, v7
	v_ashrrev_i16_sdwa v6, v1, sext(v6) dst_sel:DWORD dst_unused:UNUSED_PAD src0_sel:DWORD src1_sel:BYTE_0
	v_add_u32_sdwa v6, v7, sext(v6) dst_sel:DWORD dst_unused:UNUSED_PAD src0_sel:DWORD src1_sel:WORD_0
	v_add_lshl_u32 v7, v10, v8, 11
	v_and_b32_e32 v3, 15, v134
	v_lshl_add_u32 v132, v6, 1, v7
	v_lshlrev_b32_e32 v6, 2, v134
	v_and_b32_e32 v4, 48, v134
	v_lshlrev_b32_e32 v3, 6, v3
	v_and_b32_e32 v6, 32, v6
	v_lshlrev_b32_e32 v11, 6, v134
	v_bitop3_b32 v3, v3, v6, v4 bitop3:0x36
	v_lshlrev_b32_e32 v13, 13, v2
	v_and_or_b32 v2, v11, s39, v4
	v_add_u32_e32 v7, s35, v3
	v_add_u32_e32 v8, s36, v3
	v_add_u32_e32 v9, s37, v3
	v_add_u32_e32 v10, s38, v3
	v_and_b32_e32 v12, 0x3000, v11
	v_add_u32_e32 v3, 0x100, v3
	v_xad_u32 v4, v2, v6, s34
	v_or_b32_e32 v6, 0x800, v13
	v_or_b32_e32 v11, 0x1000, v13
	v_or_b32_e32 v14, 0x1800, v13
	v_mov_b32_e32 v2, 0
	v_add_u32_e32 v145, 0x100, v5
	v_add_u32_e32 v151, s35, v5
	v_add_u32_e32 v153, s36, v5
	v_add_u32_e32 v155, s37, v5
	v_add_u32_e32 v157, s38, v5
	v_mov_b32_e32 v133, v131
	s_mov_b32 s15, -2
	v_add_u32_e32 v144, v7, v12
	v_add_u32_e32 v138, v3, v13
	v_add_u32_e32 v137, v4, v6
	v_add_u32_e32 v136, v4, v11
	v_add_u32_e32 v135, v4, v14
	v_add_u32_e32 v143, 0xc000, v145
	v_add_u32_e32 v142, 0xe000, v145
	v_add_u32_e32 v141, v8, v12
	v_add_u32_e32 v146, 0x2000, v145
	v_add_u32_e32 v140, v9, v12
	v_add_u32_e32 v147, 0x4000, v145
	v_add_u32_e32 v148, 0x6000, v145
	v_add_u32_e32 v139, v10, v12
	v_add_u32_e32 v149, 0x8000, v145
	v_add_u32_e32 v150, 0xa000, v145
	v_add_u32_e32 v152, 0x2000, v151
	v_add_u32_e32 v154, 0x2000, v153
	v_add_u32_e32 v156, 0x2000, v155
	v_add_u32_e32 v158, 0x2000, v157
	v_mov_b32_e32 v3, v2
	v_mov_b32_e32 v4, v2
	v_mov_b32_e32 v5, v2
	v_mov_b32_e32 v6, v2
	v_mov_b32_e32 v7, v2
	v_mov_b32_e32 v8, v2
	v_mov_b32_e32 v9, v2
	v_mov_b32_e32 v10, v2
	v_mov_b32_e32 v11, v2
	v_mov_b32_e32 v12, v2
	v_mov_b32_e32 v13, v2
	v_mov_b32_e32 v14, v2
	v_mov_b32_e32 v15, v2
	v_mov_b32_e32 v16, v2
	v_mov_b32_e32 v17, v2
	v_mov_b32_e32 v18, v2
	v_mov_b32_e32 v19, v2
	v_mov_b32_e32 v20, v2
	v_mov_b32_e32 v21, v2
	v_mov_b32_e32 v22, v2
	v_mov_b32_e32 v23, v2
	v_mov_b32_e32 v24, v2
	v_mov_b32_e32 v25, v2
	v_mov_b32_e32 v26, v2
	v_mov_b32_e32 v27, v2
	v_mov_b32_e32 v28, v2
	v_mov_b32_e32 v29, v2
	v_mov_b32_e32 v30, v2
	v_mov_b32_e32 v31, v2
	v_mov_b32_e32 v32, v2
	v_mov_b32_e32 v33, v2
	v_mov_b32_e32 v34, v2
	v_mov_b32_e32 v35, v2
	v_mov_b32_e32 v36, v2
	v_mov_b32_e32 v37, v2
	v_mov_b32_e32 v38, v2
	v_mov_b32_e32 v39, v2
	v_mov_b32_e32 v40, v2
	v_mov_b32_e32 v41, v2
	v_mov_b32_e32 v42, v2
	v_mov_b32_e32 v43, v2
	v_mov_b32_e32 v44, v2
	v_mov_b32_e32 v45, v2
	v_mov_b32_e32 v46, v2
	v_mov_b32_e32 v47, v2
	v_mov_b32_e32 v48, v2
	v_mov_b32_e32 v49, v2
	v_mov_b32_e32 v50, v2
	v_mov_b32_e32 v51, v2
	v_mov_b32_e32 v52, v2
	v_mov_b32_e32 v53, v2
	v_mov_b32_e32 v54, v2
	v_mov_b32_e32 v55, v2
	v_mov_b32_e32 v56, v2
	v_mov_b32_e32 v57, v2
	v_mov_b32_e32 v58, v2
	v_mov_b32_e32 v59, v2
	v_mov_b32_e32 v60, v2
	v_mov_b32_e32 v61, v2
	v_mov_b32_e32 v62, v2
	v_mov_b32_e32 v63, v2
	v_mov_b32_e32 v64, v2
	v_mov_b32_e32 v65, v2
	v_mov_b32_e32 v66, v2
	v_mov_b32_e32 v67, v2
	v_mov_b32_e32 v68, v2
	v_mov_b32_e32 v69, v2
	v_mov_b32_e32 v70, v2
	v_mov_b32_e32 v71, v2
	v_mov_b32_e32 v72, v2
	v_mov_b32_e32 v73, v2
	v_mov_b32_e32 v74, v2
	v_mov_b32_e32 v75, v2
	v_mov_b32_e32 v76, v2
	v_mov_b32_e32 v77, v2
	v_mov_b32_e32 v78, v2
	v_mov_b32_e32 v79, v2
	v_mov_b32_e32 v80, v2
	v_mov_b32_e32 v81, v2
	v_mov_b32_e32 v82, v2
	v_mov_b32_e32 v83, v2
	v_mov_b32_e32 v84, v2
	v_mov_b32_e32 v85, v2
	v_mov_b32_e32 v86, v2
	v_mov_b32_e32 v87, v2
	v_mov_b32_e32 v88, v2
	v_mov_b32_e32 v89, v2
	v_mov_b32_e32 v90, v2
	v_mov_b32_e32 v91, v2
	v_mov_b32_e32 v92, v2
	v_mov_b32_e32 v93, v2
	v_mov_b32_e32 v94, v2
	v_mov_b32_e32 v95, v2
	v_mov_b32_e32 v96, v2
	v_mov_b32_e32 v97, v2
	v_mov_b32_e32 v98, v2
	v_mov_b32_e32 v99, v2
	v_mov_b32_e32 v100, v2
	v_mov_b32_e32 v101, v2
	v_mov_b32_e32 v102, v2
	v_mov_b32_e32 v103, v2
	v_mov_b32_e32 v104, v2
	v_mov_b32_e32 v105, v2
	v_mov_b32_e32 v106, v2
	v_mov_b32_e32 v107, v2
	v_mov_b32_e32 v108, v2
	v_mov_b32_e32 v109, v2
	v_mov_b32_e32 v110, v2
	v_mov_b32_e32 v111, v2
	v_mov_b32_e32 v112, v2
	v_mov_b32_e32 v113, v2
	v_mov_b32_e32 v114, v2
	v_mov_b32_e32 v115, v2
	v_mov_b32_e32 v116, v2
	v_mov_b32_e32 v117, v2
	v_mov_b32_e32 v118, v2
	v_mov_b32_e32 v119, v2
	v_mov_b32_e32 v120, v2
	v_mov_b32_e32 v121, v2
	v_mov_b32_e32 v122, v2
	v_mov_b32_e32 v123, v2
	v_mov_b32_e32 v124, v2
	v_mov_b32_e32 v125, v2
	v_mov_b32_e32 v126, v2
	v_mov_b32_e32 v127, v2
	v_mov_b32_e32 v128, v2
	v_mov_b32_e32 v129, v2
	s_waitcnt vmcnt(0)
	s_barrier
	s_barrier

; #define GAS __attribute__((address_space(1)))
; __device__ __forceinline__ int otid() { int t = threadIdx.x; asm volatile("" : "+v"(t)); return t; }
; #define WAIT_V(n) asm volatile("s_waitcnt vmcnt(" #n ")" ::: "memory")
; #define BAR __builtin_amdgcn_s_barrier()
; template <int K, int LD = K>
; __device__ __forceinline__ void gemm_main(const GAS bf16* A, const GAS bf16* Bt, int brow, int bcol, f32x4 (&acc)[2][2][4][2]) {
;     ...
;   const int tid_ = otid();
;     ...
;   const int wid = tid_ >> 6, lane = tid_ & 63, wr = wid >> 2, wc = wid & 3, fr = lane & 15, fq = lane >> 4;
; #pragma unroll
;   for (int a = 0; a < 2; ++a)
; #pragma unroll
;     for (int b = 0; b < 2; ++b)
; #pragma unroll
;       for (int m = 0; m < 4; ++m)
; #pragma unroll
;         for (int n = 0; n < 2; ++n) acc[a][b][m][n] = f32x4{0.f, 0.f, 0.f, 0.f};
;   bf16x8 At[4][2], B0[2][2], B1[2][2];
;   unsigned so0, so1;
;   { int r_, c_; stage_rc(tid_ * 16, r_, c_); so0 = (unsigned)(r_ * LD + c_) * 2u; stage_rc(tid_ * 16 + 8192, r_, c_); so1 = (unsigned)(r_ * LD + c_) * 2u; }
;   const GAS char* pA0 = (const GAS char*)A + (long)brow * LD * 2; const GAS char* pA1 = pA0 + (long)HALF * LD * 2;
;   const GAS char* pB0 = (const GAS char*)Bt + (long)bcol * LD * 2; const GAS char* pB1 = pB0 + (long)HALF * LD * 2;
;   asm volatile("" : "+s"(pA0), "+s"(pA1), "+s"(pB0), "+s"(pB1));
;   constexpr int nt = K / BK;
;   static_assert(K % 128 == 0 && K >= 256, "K");
;   if (wr == 1) BAR;
;   WAIT_V(0); BAR;
;   BAR;
.LBB0_883:
	s_or_b64 exec, exec, s[22:23]
	v_bfe_i32 v7, v135, 27, 1
	v_lshlrev_b32_e32 v5, 4, v135
	v_lshrrev_b32_e32 v7, 22, v7
	v_add_u32_e32 v7, v5, v7
	v_and_b32_e32 v7, 0xfffffc00, v7
	v_sub_u32_e32 v7, v5, v7
	v_lshrrev_b32_e32 v8, 4, v7
	v_bitop3_b32 v8, v8, v7, 32 bitop3:0x6c
	v_ashrrev_i32_e32 v7, 31, v7
	v_ashrrev_i32_e32 v6, 31, v135
	v_lshrrev_b32_e32 v7, 26, v7
	v_lshrrev_b32_e32 v6, 26, v6
	v_add_u32_e32 v7, v8, v7
	v_add_u32_e32 v6, v135, v6
	v_ashrrev_i32_e32 v7, 6, v7
	v_ashrrev_i32_e32 v6, 6, v6
	v_mul_i32_i24_e32 v10, 64, v7
	v_lshlrev_b32_e32 v9, 3, v6
	v_lshlrev_b32_e32 v6, 5, v6
	v_sub_u32_e32 v8, v8, v10
	v_and_b32_e32 v9, 0x1ffff0, v9
	v_and_b32_e32 v6, 32, v6
	v_ashrrev_i16_sdwa v8, v1, sext(v8) dst_sel:DWORD dst_unused:UNUSED_PAD src0_sel:DWORD src1_sel:BYTE_0
	v_add_u32_sdwa v6, v6, sext(v8) dst_sel:DWORD dst_unused:UNUSED_PAD src0_sel:DWORD src1_sel:WORD_0
	v_add_lshl_u32 v7, v7, v9, 11
	v_lshl_add_u32 v130, v6, 1, v7
	v_add_u32_e32 v6, 0x2000, v5
	v_ashrrev_i32_e32 v7, 31, v6
	v_lshrrev_b32_e32 v7, 22, v7
	v_add_u32_e32 v7, v6, v7
	v_ashrrev_i32_e32 v7, 10, v7
	v_mul_i32_i24_e32 v8, 0x400, v7
	v_sub_u32_e32 v6, v6, v8
	v_lshrrev_b32_e32 v8, 4, v6
	v_bitop3_b32 v6, v8, v6, 32 bitop3:0x6c
	v_ashrrev_i32_e32 v9, 31, v6
	v_lshrrev_b32_e32 v9, 26, v9
	v_add_u32_e32 v9, v6, v9
	v_lshrrev_b32_e32 v10, 6, v9
	v_and_b32_e32 v9, 0xc0, v9
	v_lshlrev_b32_e32 v8, 3, v7
	v_lshlrev_b32_e32 v7, 5, v7
	v_sub_u32_e32 v6, v6, v9
	v_and_b32_e32 v8, 0x1ffff0, v8
	v_and_b32_e32 v7, 32, v7
	v_ashrrev_i16_sdwa v6, v1, sext(v6) dst_sel:DWORD dst_unused:UNUSED_PAD src0_sel:DWORD src1_sel:BYTE_0
	v_add_u32_sdwa v6, v7, sext(v6) dst_sel:DWORD dst_unused:UNUSED_PAD src0_sel:DWORD src1_sel:WORD_0
	v_add_lshl_u32 v7, v10, v8, 11
	v_and_b32_e32 v3, 15, v135
	v_lshl_add_u32 v132, v6, 1, v7
	v_lshlrev_b32_e32 v6, 2, v135
	v_and_b32_e32 v4, 48, v135
	v_lshlrev_b32_e32 v3, 6, v3
	v_and_b32_e32 v6, 32, v6
	v_lshlrev_b32_e32 v11, 6, v135
	v_bitop3_b32 v3, v3, v6, v4 bitop3:0x36
	v_lshlrev_b32_e32 v13, 13, v2
	v_and_or_b32 v2, v11, s38, v4
	v_add_u32_e32 v7, s29, v3
	v_add_u32_e32 v8, s30, v3
	v_add_u32_e32 v9, s31, v3
	v_add_u32_e32 v10, s33, v3
	v_and_b32_e32 v12, 0x3000, v11
	v_add_u32_e32 v3, 0x100, v3
	v_xad_u32 v4, v2, v6, s34
	v_or_b32_e32 v6, 0x800, v13
	v_or_b32_e32 v11, 0x1000, v13
	v_or_b32_e32 v14, 0x1800, v13
	v_mov_b32_e32 v2, 0
	v_add_u32_e32 v146, 0x100, v5
	v_add_u32_e32 v152, s29, v5
	v_add_u32_e32 v154, s30, v5
	v_add_u32_e32 v156, s31, v5
	v_add_u32_e32 v158, s33, v5
	v_mov_b32_e32 v133, v131
	s_mov_b32 s15, -2
	v_add_u32_e32 v145, v7, v12
	v_add_u32_e32 v139, v3, v13
	v_add_u32_e32 v138, v4, v6
	v_add_u32_e32 v137, v4, v11
	v_add_u32_e32 v136, v4, v14
	v_add_u32_e32 v144, 0xc000, v146
	v_add_u32_e32 v143, 0xe000, v146
	v_add_u32_e32 v142, v8, v12
	v_add_u32_e32 v147, 0x2000, v146
	v_add_u32_e32 v141, v9, v12
	v_add_u32_e32 v148, 0x4000, v146
	v_add_u32_e32 v149, 0x6000, v146
	v_add_u32_e32 v140, v10, v12
	v_add_u32_e32 v150, 0x8000, v146
	v_add_u32_e32 v151, 0xa000, v146
	v_add_u32_e32 v153, 0x2000, v152
	v_add_u32_e32 v155, 0x2000, v154
	v_add_u32_e32 v157, 0x2000, v156
	v_add_u32_e32 v159, 0x2000, v158
	v_mov_b32_e32 v3, v2
	v_mov_b32_e32 v4, v2
	v_mov_b32_e32 v5, v2
	v_mov_b32_e32 v6, v2
	v_mov_b32_e32 v7, v2
	v_mov_b32_e32 v8, v2
	v_mov_b32_e32 v9, v2
	v_mov_b32_e32 v10, v2
	v_mov_b32_e32 v11, v2
	v_mov_b32_e32 v12, v2
	v_mov_b32_e32 v13, v2
	v_mov_b32_e32 v14, v2
	v_mov_b32_e32 v15, v2
	v_mov_b32_e32 v16, v2
	v_mov_b32_e32 v17, v2
	v_mov_b32_e32 v18, v2
	v_mov_b32_e32 v19, v2
	v_mov_b32_e32 v20, v2
	v_mov_b32_e32 v21, v2
	v_mov_b32_e32 v22, v2
	v_mov_b32_e32 v23, v2
	v_mov_b32_e32 v24, v2
	v_mov_b32_e32 v25, v2
	v_mov_b32_e32 v26, v2
	v_mov_b32_e32 v27, v2
	v_mov_b32_e32 v28, v2
	v_mov_b32_e32 v29, v2
	v_mov_b32_e32 v30, v2
	v_mov_b32_e32 v31, v2
	v_mov_b32_e32 v32, v2
	v_mov_b32_e32 v33, v2
	v_mov_b32_e32 v34, v2
	v_mov_b32_e32 v35, v2
	v_mov_b32_e32 v36, v2
	v_mov_b32_e32 v37, v2
	v_mov_b32_e32 v38, v2
	v_mov_b32_e32 v39, v2
	v_mov_b32_e32 v40, v2
	v_mov_b32_e32 v41, v2
	v_mov_b32_e32 v42, v2
	v_mov_b32_e32 v43, v2
	v_mov_b32_e32 v44, v2
	v_mov_b32_e32 v45, v2
	v_mov_b32_e32 v46, v2
	v_mov_b32_e32 v47, v2
	v_mov_b32_e32 v48, v2
	v_mov_b32_e32 v49, v2
	v_mov_b32_e32 v50, v2
	v_mov_b32_e32 v51, v2
	v_mov_b32_e32 v52, v2
	v_mov_b32_e32 v53, v2
	v_mov_b32_e32 v54, v2
	v_mov_b32_e32 v55, v2
	v_mov_b32_e32 v56, v2
	v_mov_b32_e32 v57, v2
	v_mov_b32_e32 v58, v2
	v_mov_b32_e32 v59, v2
	v_mov_b32_e32 v60, v2
	v_mov_b32_e32 v61, v2
	v_mov_b32_e32 v62, v2
	v_mov_b32_e32 v63, v2
	v_mov_b32_e32 v64, v2
	v_mov_b32_e32 v65, v2
	v_mov_b32_e32 v66, v2
	v_mov_b32_e32 v67, v2
	v_mov_b32_e32 v68, v2
	v_mov_b32_e32 v69, v2
	v_mov_b32_e32 v70, v2
	v_mov_b32_e32 v71, v2
	v_mov_b32_e32 v72, v2
	v_mov_b32_e32 v73, v2
	v_mov_b32_e32 v74, v2
	v_mov_b32_e32 v75, v2
	v_mov_b32_e32 v76, v2
	v_mov_b32_e32 v77, v2
	v_mov_b32_e32 v78, v2
	v_mov_b32_e32 v79, v2
	v_mov_b32_e32 v80, v2
	v_mov_b32_e32 v81, v2
	v_mov_b32_e32 v82, v2
	v_mov_b32_e32 v83, v2
	v_mov_b32_e32 v84, v2
	v_mov_b32_e32 v85, v2
	v_mov_b32_e32 v86, v2
	v_mov_b32_e32 v87, v2
	v_mov_b32_e32 v88, v2
	v_mov_b32_e32 v89, v2
	v_mov_b32_e32 v90, v2
	v_mov_b32_e32 v91, v2
	v_mov_b32_e32 v92, v2
	v_mov_b32_e32 v93, v2
	v_mov_b32_e32 v94, v2
	v_mov_b32_e32 v95, v2
	v_mov_b32_e32 v96, v2
	v_mov_b32_e32 v97, v2
	v_mov_b32_e32 v98, v2
	v_mov_b32_e32 v99, v2
	v_mov_b32_e32 v100, v2
	v_mov_b32_e32 v101, v2
	v_mov_b32_e32 v102, v2
	v_mov_b32_e32 v103, v2
	v_mov_b32_e32 v104, v2
	v_mov_b32_e32 v105, v2
	v_mov_b32_e32 v106, v2
	v_mov_b32_e32 v107, v2
	v_mov_b32_e32 v108, v2
	v_mov_b32_e32 v109, v2
	v_mov_b32_e32 v110, v2
	v_mov_b32_e32 v111, v2
	v_mov_b32_e32 v112, v2
	v_mov_b32_e32 v113, v2
	v_mov_b32_e32 v114, v2
	v_mov_b32_e32 v115, v2
	v_mov_b32_e32 v116, v2
	v_mov_b32_e32 v117, v2
	v_mov_b32_e32 v118, v2
	v_mov_b32_e32 v119, v2
	v_mov_b32_e32 v120, v2
	v_mov_b32_e32 v121, v2
	v_mov_b32_e32 v122, v2
	v_mov_b32_e32 v123, v2
	v_mov_b32_e32 v124, v2
	v_mov_b32_e32 v125, v2
	v_mov_b32_e32 v126, v2
	v_mov_b32_e32 v127, v2
	v_mov_b32_e32 v128, v2
	v_mov_b32_e32 v129, v2
	s_waitcnt vmcnt(0)
	s_barrier
	s_barrier

; #define GAS __attribute__((address_space(1)))
; __device__ __forceinline__ int otid() { int t = threadIdx.x; asm volatile("" : "+v"(t)); return t; }
; #define WAIT_V(n) asm volatile("s_waitcnt vmcnt(" #n ")" ::: "memory")
; #define BAR __builtin_amdgcn_s_barrier()
; template <int K, int LD = K>
; __device__ __forceinline__ void gemm_main(const GAS bf16* A, const GAS bf16* Bt, int brow, int bcol, f32x4 (&acc)[2][2][4][2]) {
;     ...
;   const int tid_ = otid();
;     ...
;   const int wid = tid_ >> 6, lane = tid_ & 63, wr = wid >> 2, wc = wid & 3, fr = lane & 15, fq = lane >> 4;
; #pragma unroll
;   for (int a = 0; a < 2; ++a)
; #pragma unroll
;     for (int b = 0; b < 2; ++b)
; #pragma unroll
;       for (int m = 0; m < 4; ++m)
; #pragma unroll
;         for (int n = 0; n < 2; ++n) acc[a][b][m][n] = f32x4{0.f, 0.f, 0.f, 0.f};
;   bf16x8 At[4][2], B0[2][2], B1[2][2];
;   unsigned so0, so1;
;   { int r_, c_; stage_rc(tid_ * 16, r_, c_); so0 = (unsigned)(r_ * LD + c_) * 2u; stage_rc(tid_ * 16 + 8192, r_, c_); so1 = (unsigned)(r_ * LD + c_) * 2u; }
;   const GAS char* pA0 = (const GAS char*)A + (long)brow * LD * 2; const GAS char* pA1 = pA0 + (long)HALF * LD * 2;
;   const GAS char* pB0 = (const GAS char*)Bt + (long)bcol * LD * 2; const GAS char* pB1 = pB0 + (long)HALF * LD * 2;
;   asm volatile("" : "+s"(pA0), "+s"(pA1), "+s"(pB0), "+s"(pB1));
;   constexpr int nt = K / BK;
;   static_assert(K % 128 == 0 && K >= 256, "K");
;   if (wr == 1) BAR;
;   WAIT_V(0); BAR;
;   BAR;
.LBB0_1104:
	s_or_b64 exec, exec, s[22:23]
	v_bfe_i32 v7, v134, 27, 1
	v_lshlrev_b32_e32 v5, 4, v134
	v_lshrrev_b32_e32 v7, 22, v7
	v_add_u32_e32 v7, v5, v7
	v_and_b32_e32 v7, 0xfffffc00, v7
	v_ashrrev_i32_e32 v6, 31, v134
	v_sub_u32_e32 v7, v5, v7
	v_lshrrev_b32_e32 v6, 26, v6
	v_lshrrev_b32_e32 v8, 4, v7
	v_add_u32_e32 v6, v134, v6
	v_bitop3_b32 v8, v8, v7, 32 bitop3:0x6c
	v_ashrrev_i32_e32 v7, 31, v7
	v_ashrrev_i32_e32 v6, 6, v6
	v_lshrrev_b32_e32 v7, 26, v7
	v_lshlrev_b32_e32 v9, 3, v6
	v_add_u32_e32 v7, v8, v7
	v_and_b32_e32 v9, 0x3fffff0, v9
	v_ashrrev_i32_e32 v7, 6, v7
	v_add_u32_e32 v9, v7, v9
	v_mul_i32_i24_e32 v7, 64, v7
	v_sub_u32_e32 v7, v8, v7
	v_lshlrev_b32_e32 v6, 5, v6
	v_ashrrev_i16_sdwa v7, v1, sext(v7) dst_sel:DWORD dst_unused:UNUSED_PAD src0_sel:DWORD src1_sel:BYTE_0
	v_mul_lo_u32 v8, v9, s31
	v_bfe_i32 v7, v7, 0, 16
	v_and_or_b32 v6, v6, 32, v8
	v_add_lshl_u32 v130, v6, v7, 1
	v_add_u32_e32 v6, 0x2000, v5
	v_ashrrev_i32_e32 v7, 31, v6
	v_lshrrev_b32_e32 v7, 22, v7
	v_add_u32_e32 v7, v6, v7
	v_ashrrev_i32_e32 v7, 10, v7
	v_mul_i32_i24_e32 v8, 0x400, v7
	v_sub_u32_e32 v6, v6, v8
	v_lshrrev_b32_e32 v8, 4, v6
	v_bitop3_b32 v6, v8, v6, 32 bitop3:0x6c
	v_ashrrev_i32_e32 v9, 31, v6
	v_lshrrev_b32_e32 v9, 26, v9
	v_lshlrev_b32_e32 v8, 3, v7
	v_add_u32_e32 v9, v6, v9
	v_and_b32_e32 v8, 0x3fffff0, v8
	v_lshrrev_b32_e32 v10, 6, v9
	v_and_b32_e32 v9, 0xc0, v9
	v_add_u32_e32 v8, v10, v8
	v_sub_u32_e32 v6, v6, v9
	v_lshlrev_b32_e32 v7, 5, v7
	v_ashrrev_i16_sdwa v6, v1, sext(v6) dst_sel:DWORD dst_unused:UNUSED_PAD src0_sel:DWORD src1_sel:BYTE_0
	v_mul_lo_u32 v8, v8, s31
	v_bfe_i32 v6, v6, 0, 16
	v_and_or_b32 v7, v7, 32, v8
	v_and_b32_e32 v3, 15, v134
	v_add_lshl_u32 v132, v7, v6, 1
	v_lshlrev_b32_e32 v6, 2, v134
	v_and_b32_e32 v4, 48, v134
	v_lshlrev_b32_e32 v3, 6, v3
	v_and_b32_e32 v6, 32, v6
	v_lshlrev_b32_e32 v11, 6, v134
	v_bitop3_b32 v3, v3, v6, v4 bitop3:0x36
	v_lshlrev_b32_e32 v13, 13, v2
	v_and_or_b32 v2, v11, s38, v4
	v_add_u32_e32 v7, s34, v3
	v_add_u32_e32 v8, s35, v3
	v_add_u32_e32 v9, s36, v3
	v_add_u32_e32 v10, s37, v3
	v_and_b32_e32 v12, 0x3000, v11
	v_add_u32_e32 v3, 0x100, v3
	v_xad_u32 v4, v2, v6, s33
	v_or_b32_e32 v6, 0x800, v13
	v_or_b32_e32 v11, 0x1000, v13
	v_or_b32_e32 v14, 0x1800, v13
	v_mov_b32_e32 v2, 0
	v_add_u32_e32 v145, 0x100, v5
	v_add_u32_e32 v151, s34, v5
	v_add_u32_e32 v153, s35, v5
	v_add_u32_e32 v155, s36, v5
	v_add_u32_e32 v157, s37, v5
	v_mov_b32_e32 v133, v131
	s_mov_b32 s22, -2
	v_add_u32_e32 v144, v7, v12
	v_add_u32_e32 v138, v3, v13
	v_add_u32_e32 v137, v4, v6
	v_add_u32_e32 v136, v4, v11
	v_add_u32_e32 v135, v4, v14
	v_add_u32_e32 v143, 0xc000, v145
	v_add_u32_e32 v142, 0xe000, v145
	v_add_u32_e32 v141, v8, v12
	v_add_u32_e32 v146, 0x2000, v145
	v_add_u32_e32 v140, v9, v12
	v_add_u32_e32 v147, 0x4000, v145
	v_add_u32_e32 v148, 0x6000, v145
	v_add_u32_e32 v139, v10, v12
	v_add_u32_e32 v149, 0x8000, v145
	v_add_u32_e32 v150, 0xa000, v145
	v_add_u32_e32 v152, 0x2000, v151
	v_add_u32_e32 v154, 0x2000, v153
	v_add_u32_e32 v156, 0x2000, v155
	v_add_u32_e32 v158, 0x2000, v157
	v_mov_b32_e32 v3, v2
	v_mov_b32_e32 v4, v2
	v_mov_b32_e32 v5, v2
	v_mov_b32_e32 v6, v2
	v_mov_b32_e32 v7, v2
	v_mov_b32_e32 v8, v2
	v_mov_b32_e32 v9, v2
	v_mov_b32_e32 v10, v2
	v_mov_b32_e32 v11, v2
	v_mov_b32_e32 v12, v2
	v_mov_b32_e32 v13, v2
	v_mov_b32_e32 v14, v2
	v_mov_b32_e32 v15, v2
	v_mov_b32_e32 v16, v2
	v_mov_b32_e32 v17, v2
	v_mov_b32_e32 v18, v2
	v_mov_b32_e32 v19, v2
	v_mov_b32_e32 v20, v2
	v_mov_b32_e32 v21, v2
	v_mov_b32_e32 v22, v2
	v_mov_b32_e32 v23, v2
	v_mov_b32_e32 v24, v2
	v_mov_b32_e32 v25, v2
	v_mov_b32_e32 v26, v2
	v_mov_b32_e32 v27, v2
	v_mov_b32_e32 v28, v2
	v_mov_b32_e32 v29, v2
	v_mov_b32_e32 v30, v2
	v_mov_b32_e32 v31, v2
	v_mov_b32_e32 v32, v2
	v_mov_b32_e32 v33, v2
	v_mov_b32_e32 v34, v2
	v_mov_b32_e32 v35, v2
	v_mov_b32_e32 v36, v2
	v_mov_b32_e32 v37, v2
	v_mov_b32_e32 v38, v2
	v_mov_b32_e32 v39, v2
	v_mov_b32_e32 v40, v2
	v_mov_b32_e32 v41, v2
	v_mov_b32_e32 v42, v2
	v_mov_b32_e32 v43, v2
	v_mov_b32_e32 v44, v2
	v_mov_b32_e32 v45, v2
	v_mov_b32_e32 v46, v2
	v_mov_b32_e32 v47, v2
	v_mov_b32_e32 v48, v2
	v_mov_b32_e32 v49, v2
	v_mov_b32_e32 v50, v2
	v_mov_b32_e32 v51, v2
	v_mov_b32_e32 v52, v2
	v_mov_b32_e32 v53, v2
	v_mov_b32_e32 v54, v2
	v_mov_b32_e32 v55, v2
	v_mov_b32_e32 v56, v2
	v_mov_b32_e32 v57, v2
	v_mov_b32_e32 v58, v2
	v_mov_b32_e32 v59, v2
	v_mov_b32_e32 v60, v2
	v_mov_b32_e32 v61, v2
	v_mov_b32_e32 v62, v2
	v_mov_b32_e32 v63, v2
	v_mov_b32_e32 v64, v2
	v_mov_b32_e32 v65, v2
	v_mov_b32_e32 v66, v2
	v_mov_b32_e32 v67, v2
	v_mov_b32_e32 v68, v2
	v_mov_b32_e32 v69, v2
	v_mov_b32_e32 v70, v2
	v_mov_b32_e32 v71, v2
	v_mov_b32_e32 v72, v2
	v_mov_b32_e32 v73, v2
	v_mov_b32_e32 v74, v2
	v_mov_b32_e32 v75, v2
	v_mov_b32_e32 v76, v2
	v_mov_b32_e32 v77, v2
	v_mov_b32_e32 v78, v2
	v_mov_b32_e32 v79, v2
	v_mov_b32_e32 v80, v2
	v_mov_b32_e32 v81, v2
	v_mov_b32_e32 v82, v2
	v_mov_b32_e32 v83, v2
	v_mov_b32_e32 v84, v2
	v_mov_b32_e32 v85, v2
	v_mov_b32_e32 v86, v2
	v_mov_b32_e32 v87, v2
	v_mov_b32_e32 v88, v2
	v_mov_b32_e32 v89, v2
	v_mov_b32_e32 v90, v2
	v_mov_b32_e32 v91, v2
	v_mov_b32_e32 v92, v2
	v_mov_b32_e32 v93, v2
	v_mov_b32_e32 v94, v2
	v_mov_b32_e32 v95, v2
	v_mov_b32_e32 v96, v2
	v_mov_b32_e32 v97, v2
	v_mov_b32_e32 v98, v2
	v_mov_b32_e32 v99, v2
	v_mov_b32_e32 v100, v2
	v_mov_b32_e32 v101, v2
	v_mov_b32_e32 v102, v2
	v_mov_b32_e32 v103, v2
	v_mov_b32_e32 v104, v2
	v_mov_b32_e32 v105, v2
	v_mov_b32_e32 v106, v2
	v_mov_b32_e32 v107, v2
	v_mov_b32_e32 v108, v2
	v_mov_b32_e32 v109, v2
	v_mov_b32_e32 v110, v2
	v_mov_b32_e32 v111, v2
	v_mov_b32_e32 v112, v2
	v_mov_b32_e32 v113, v2
	v_mov_b32_e32 v114, v2
	v_mov_b32_e32 v115, v2
	v_mov_b32_e32 v116, v2
	v_mov_b32_e32 v117, v2
	v_mov_b32_e32 v118, v2
	v_mov_b32_e32 v119, v2
	v_mov_b32_e32 v120, v2
	v_mov_b32_e32 v121, v2
	v_mov_b32_e32 v122, v2
	v_mov_b32_e32 v123, v2
	v_mov_b32_e32 v124, v2
	v_mov_b32_e32 v125, v2
	v_mov_b32_e32 v126, v2
	v_mov_b32_e32 v127, v2
	v_mov_b32_e32 v128, v2
	v_mov_b32_e32 v129, v2
	s_waitcnt vmcnt(0)
	s_barrier
	s_barrier

; #define GAS __attribute__((address_space(1)))
; __device__ __forceinline__ int otid() { int t = threadIdx.x; asm volatile("" : "+v"(t)); return t; }
; #define WAIT_V(n) asm volatile("s_waitcnt vmcnt(" #n ")" ::: "memory")
; #define BAR __builtin_amdgcn_s_barrier()
; template <int K, int LD = K>
; __device__ __forceinline__ void gemm_main(const GAS bf16* A, const GAS bf16* Bt, int brow, int bcol, f32x4 (&acc)[2][2][4][2]) {
;     ...
;   const int tid_ = otid();
;     ...
;   const int wid = tid_ >> 6, lane = tid_ & 63, wr = wid >> 2, wc = wid & 3, fr = lane & 15, fq = lane >> 4;
; #pragma unroll
;   for (int a = 0; a < 2; ++a)
; #pragma unroll
;     for (int b = 0; b < 2; ++b)
; #pragma unroll
;       for (int m = 0; m < 4; ++m)
; #pragma unroll
;         for (int n = 0; n < 2; ++n) acc[a][b][m][n] = f32x4{0.f, 0.f, 0.f, 0.f};
;   bf16x8 At[4][2], B0[2][2], B1[2][2];
;   unsigned so0, so1;
;   { int r_, c_; stage_rc(tid_ * 16, r_, c_); so0 = (unsigned)(r_ * LD + c_) * 2u; stage_rc(tid_ * 16 + 8192, r_, c_); so1 = (unsigned)(r_ * LD + c_) * 2u; }
;   const GAS char* pA0 = (const GAS char*)A + (long)brow * LD * 2; const GAS char* pA1 = pA0 + (long)HALF * LD * 2;
;   const GAS char* pB0 = (const GAS char*)Bt + (long)bcol * LD * 2; const GAS char* pB1 = pB0 + (long)HALF * LD * 2;
;   asm volatile("" : "+s"(pA0), "+s"(pA1), "+s"(pB0), "+s"(pB1));
;   constexpr int nt = K / BK;
;   static_assert(K % 128 == 0 && K >= 256, "K");
;   if (wr == 1) BAR;
;   WAIT_V(0); BAR;
;   BAR;
.LBB0_1225:
	s_or_b64 exec, exec, s[30:31]
	v_bfe_i32 v6, v132, 27, 1
	v_lshlrev_b32_e32 v141, 4, v132
	v_lshrrev_b32_e32 v6, 22, v6
	v_add_u32_e32 v6, v141, v6
	v_and_b32_e32 v6, 0xfffffc00, v6
	v_sub_u32_e32 v6, v141, v6
	v_lshrrev_b32_e32 v7, 4, v6
	v_bitop3_b32 v7, v7, v6, 32 bitop3:0x6c
	v_ashrrev_i32_e32 v6, 31, v6
	v_ashrrev_i32_e32 v5, 31, v132
	v_lshrrev_b32_e32 v6, 26, v6
	v_lshrrev_b32_e32 v5, 26, v5
	v_add_u32_e32 v6, v7, v6
	v_add_u32_e32 v5, v132, v5
	v_ashrrev_i32_e32 v6, 6, v6
	v_ashrrev_i32_e32 v5, 6, v5
	v_mul_i32_i24_e32 v9, 64, v6
	v_lshlrev_b32_e32 v8, 3, v5
	v_lshlrev_b32_e32 v5, 5, v5
	v_sub_u32_e32 v7, v7, v9
	v_and_b32_e32 v8, 0x1ffff0, v8
	v_and_b32_e32 v5, 32, v5
	v_ashrrev_i16_sdwa v7, v1, sext(v7) dst_sel:DWORD dst_unused:UNUSED_PAD src0_sel:DWORD src1_sel:BYTE_0
	v_add_u32_sdwa v5, v5, sext(v7) dst_sel:DWORD dst_unused:UNUSED_PAD src0_sel:DWORD src1_sel:WORD_0
	v_add_lshl_u32 v6, v6, v8, 11
	v_lshl_add_u32 v138, v5, 1, v6
	v_add_u32_e32 v5, 0x2000, v141
	v_ashrrev_i32_e32 v6, 31, v5
	v_lshrrev_b32_e32 v6, 22, v6
	v_add_u32_e32 v6, v5, v6
	v_ashrrev_i32_e32 v6, 10, v6
	v_mul_i32_i24_e32 v7, 0x400, v6
	v_sub_u32_e32 v5, v5, v7
	v_lshrrev_b32_e32 v7, 4, v5
	v_bitop3_b32 v5, v7, v5, 32 bitop3:0x6c
	v_ashrrev_i32_e32 v8, 31, v5
	v_lshrrev_b32_e32 v8, 26, v8
	v_add_u32_e32 v8, v5, v8
	v_lshrrev_b32_e32 v9, 6, v8
	v_and_b32_e32 v8, 0xc0, v8
	v_lshlrev_b32_e32 v7, 3, v6
	v_lshlrev_b32_e32 v6, 5, v6
	v_sub_u32_e32 v5, v5, v8
	v_and_b32_e32 v7, 0x1ffff0, v7
	v_and_b32_e32 v6, 32, v6
	v_ashrrev_i16_sdwa v5, v1, sext(v5) dst_sel:DWORD dst_unused:UNUSED_PAD src0_sel:DWORD src1_sel:BYTE_0
	v_add_u32_sdwa v5, v6, sext(v5) dst_sel:DWORD dst_unused:UNUSED_PAD src0_sel:DWORD src1_sel:WORD_0
	v_add_lshl_u32 v6, v9, v7, 11
	v_and_b32_e32 v3, 15, v132
	v_lshl_add_u32 v130, v5, 1, v6
	v_lshlrev_b32_e32 v5, 2, v132
	v_and_b32_e32 v4, 48, v132
	v_lshlrev_b32_e32 v3, 6, v3
	v_and_b32_e32 v5, 32, v5
	v_lshlrev_b32_e32 v10, 6, v132
	v_bitop3_b32 v3, v3, v5, v4 bitop3:0x36
	v_lshlrev_b32_e32 v12, 13, v2
	v_and_or_b32 v2, v10, s46, v4
	v_add_u32_e32 v6, s38, v3
	v_add_u32_e32 v7, s39, v3
	v_add_u32_e32 v8, s40, v3
	v_add_u32_e32 v9, s41, v3
	v_and_b32_e32 v11, 0x3000, v10
	v_add_u32_e32 v3, 0x100, v3
	v_xad_u32 v4, v2, v5, s42
	v_or_b32_e32 v5, 0x800, v12
	v_or_b32_e32 v10, 0x1000, v12
	v_or_b32_e32 v13, 0x1800, v12
	v_mov_b32_e32 v2, 0
	v_mov_b32_e32 v131, v139
	s_mov_b32 s21, -2
	v_add_u32_e32 v143, v6, v11
	v_add_u32_e32 v136, v3, v12
	v_add_u32_e32 v135, v4, v5
	v_add_u32_e32 v134, v4, v10
	v_add_u32_e32 v133, v4, v13
	v_add_u32_e32 v142, v7, v11
	v_add_u32_e32 v140, v8, v11
	v_add_u32_e32 v137, v9, v11
	v_mov_b32_e32 v3, v2
	v_mov_b32_e32 v4, v2
	v_mov_b32_e32 v5, v2
	v_mov_b32_e32 v6, v2
	v_mov_b32_e32 v7, v2
	v_mov_b32_e32 v8, v2
	v_mov_b32_e32 v9, v2
	v_mov_b32_e32 v10, v2
	v_mov_b32_e32 v11, v2
	v_mov_b32_e32 v12, v2
	v_mov_b32_e32 v13, v2
	v_mov_b32_e32 v14, v2
	v_mov_b32_e32 v15, v2
	v_mov_b32_e32 v16, v2
	v_mov_b32_e32 v17, v2
	v_mov_b32_e32 v18, v2
	v_mov_b32_e32 v19, v2
	v_mov_b32_e32 v20, v2
	v_mov_b32_e32 v21, v2
	v_mov_b32_e32 v22, v2
	v_mov_b32_e32 v23, v2
	v_mov_b32_e32 v24, v2
	v_mov_b32_e32 v25, v2
	v_mov_b32_e32 v26, v2
	v_mov_b32_e32 v27, v2
	v_mov_b32_e32 v28, v2
	v_mov_b32_e32 v29, v2
	v_mov_b32_e32 v30, v2
	v_mov_b32_e32 v31, v2
	v_mov_b32_e32 v32, v2
	v_mov_b32_e32 v33, v2
	v_mov_b32_e32 v34, v2
	v_mov_b32_e32 v35, v2
	v_mov_b32_e32 v36, v2
	v_mov_b32_e32 v37, v2
	v_mov_b32_e32 v38, v2
	v_mov_b32_e32 v39, v2
	v_mov_b32_e32 v40, v2
	v_mov_b32_e32 v41, v2
	v_mov_b32_e32 v42, v2
	v_mov_b32_e32 v43, v2
	v_mov_b32_e32 v44, v2
	v_mov_b32_e32 v45, v2
	v_mov_b32_e32 v46, v2
	v_mov_b32_e32 v47, v2
	v_mov_b32_e32 v48, v2
	v_mov_b32_e32 v49, v2
	v_mov_b32_e32 v50, v2
	v_mov_b32_e32 v51, v2
	v_mov_b32_e32 v52, v2
	v_mov_b32_e32 v53, v2
	v_mov_b32_e32 v54, v2
	v_mov_b32_e32 v55, v2
	v_mov_b32_e32 v56, v2
	v_mov_b32_e32 v57, v2
	v_mov_b32_e32 v58, v2
	v_mov_b32_e32 v59, v2
	v_mov_b32_e32 v60, v2
	v_mov_b32_e32 v61, v2
	v_mov_b32_e32 v62, v2
	v_mov_b32_e32 v63, v2
	v_mov_b32_e32 v64, v2
	v_mov_b32_e32 v65, v2
	v_mov_b32_e32 v66, v2
	v_mov_b32_e32 v67, v2
	v_mov_b32_e32 v68, v2
	v_mov_b32_e32 v69, v2
	v_mov_b32_e32 v70, v2
	v_mov_b32_e32 v71, v2
	v_mov_b32_e32 v72, v2
	v_mov_b32_e32 v73, v2
	v_mov_b32_e32 v74, v2
	v_mov_b32_e32 v75, v2
	v_mov_b32_e32 v76, v2
	v_mov_b32_e32 v77, v2
	v_mov_b32_e32 v78, v2
	v_mov_b32_e32 v79, v2
	v_mov_b32_e32 v80, v2
	v_mov_b32_e32 v81, v2
	v_mov_b32_e32 v82, v2
	v_mov_b32_e32 v83, v2
	v_mov_b32_e32 v84, v2
	v_mov_b32_e32 v85, v2
	v_mov_b32_e32 v86, v2
	v_mov_b32_e32 v87, v2
	v_mov_b32_e32 v88, v2
	v_mov_b32_e32 v89, v2
	v_mov_b32_e32 v90, v2
	v_mov_b32_e32 v91, v2
	v_mov_b32_e32 v92, v2
	v_mov_b32_e32 v93, v2
	v_mov_b32_e32 v94, v2
	v_mov_b32_e32 v95, v2
	v_mov_b32_e32 v96, v2
	v_mov_b32_e32 v97, v2
	v_mov_b32_e32 v98, v2
	v_mov_b32_e32 v99, v2
	v_mov_b32_e32 v100, v2
	v_mov_b32_e32 v101, v2
	v_mov_b32_e32 v102, v2
	v_mov_b32_e32 v103, v2
	v_mov_b32_e32 v104, v2
	v_mov_b32_e32 v105, v2
	v_mov_b32_e32 v106, v2
	v_mov_b32_e32 v107, v2
	v_mov_b32_e32 v108, v2
	v_mov_b32_e32 v109, v2
	v_mov_b32_e32 v110, v2
	v_mov_b32_e32 v111, v2
	v_mov_b32_e32 v112, v2
	v_mov_b32_e32 v113, v2
	v_mov_b32_e32 v114, v2
	v_mov_b32_e32 v115, v2
	v_mov_b32_e32 v116, v2
	v_mov_b32_e32 v117, v2
	v_mov_b32_e32 v118, v2
	v_mov_b32_e32 v119, v2
	v_mov_b32_e32 v120, v2
	v_mov_b32_e32 v121, v2
	v_mov_b32_e32 v122, v2
	v_mov_b32_e32 v123, v2
	v_mov_b32_e32 v124, v2
	v_mov_b32_e32 v125, v2
	v_mov_b32_e32 v126, v2
	v_mov_b32_e32 v127, v2
	v_mov_b32_e32 v128, v2
	v_mov_b32_e32 v129, v2
	s_waitcnt vmcnt(0)
	s_barrier
	s_barrier
